# MO8 MFMA order + full-cache-line LDS-DMA staging layout (8 rows x 128 B per DMA, XOR-swizzled LDS image) in the proj, w_out and gate/up GEMM loops
# baseline (speedup 1.0000x reference)
.LBB0_129:
	s_andn2_b64 vcc, exec, s[0:1]
	v_readlane_b32 s17, v251, 20
	s_cbranch_vccnz .LBB0_198
	v_readlane_b32 s2, v251, 52
	v_readlane_b32 s3, v251, 53
	v_readlane_b32 s0, v251, 21
	s_andn2_b64 vcc, exec, s[2:3]
	s_waitcnt vmcnt(0)
	v_mbcnt_lo_u32_b32 v3, -1, 0
	v_mbcnt_hi_u32_b32 v3, -1, v3
	s_cbranch_vccnz .LBB0_146
	s_lshl_b32 s26, s0, 10
	v_lshl_add_u32 v0, v3, 4, s26
	s_waitcnt vmcnt(22)
	v_add_u32_e32 v4, 0x2000, v0
	v_ashrrev_i32_e32 v2, 31, v4
	v_lshrrev_b32_e32 v2, 22, v2
	v_add_u32_e32 v2, v4, v2
	v_ashrrev_i32_e32 v2, 10, v2
	v_mul_i32_i24_e32 v5, 0x400, v2
	v_sub_u32_e32 v4, v4, v5
	v_lshrrev_b32_e32 v5, 4, v4
	v_bitop3_b32 v5, v5, v4, 32 bitop3:0x6c
	v_ashrrev_i32_e32 v4, 31, v5
	v_lshrrev_b32_e32 v4, 26, v4
	v_add_u32_e32 v6, v5, v4
	v_ashrrev_i32_e32 v4, 6, v6
	v_lshlrev_b32_e32 v7, 3, v2
	v_and_b32_e32 v6, 0xffc0, v6
	v_and_b32_e32 v7, -16, v7
	v_sub_u32_e32 v5, v5, v6
	v_add_u32_e32 v7, v4, v7
	v_lshrrev_b16_e32 v6, 7, v5
	s_waitcnt vmcnt(21)
	v_and_b32_e32 v8, 3, v4
	s_mov_b32 s2, 0x7ffe0
	v_lshrrev_b32_e32 v9, 2, v7
	v_lshlrev_b32_e32 v10, 1, v7
	v_and_b32_e32 v6, 1, v6
	v_and_or_b32 v8, v7, s2, v8
	v_and_b32_e32 v9, 4, v9
	v_and_b32_e32 v10, 24, v10
	v_add_u16_e32 v5, v5, v6
	v_or3_b32 v8, v8, v9, v10
	v_lshlrev_b32_e32 v9, 5, v2
	v_ashrrev_i16_sdwa v5, v212, sext(v5) dst_sel:DWORD dst_unused:UNUSED_PAD src0_sel:DWORD src1_sel:BYTE_0
	v_and_b32_e32 v9, 32, v9
	v_bfe_i32 v5, v5, 0, 16
	v_add_lshl_u32 v6, v9, v5, 1
	v_lshl_add_u32 v130, v8, 13, v6
	v_lshl_add_u32 v132, v7, 13, v6
	v_ashrrev_i32_e32 v6, 31, v0
	v_lshrrev_b32_e32 v6, 22, v6
	v_add_u32_e32 v6, v0, v6
	v_ashrrev_i32_e32 v6, 10, v6
	v_mul_i32_i24_e32 v7, 0x400, v6
	v_sub_u32_e32 v0, v0, v7
	v_lshrrev_b32_e32 v7, 4, v0
	v_bitop3_b32 v0, v7, v0, 32 bitop3:0x6c
	v_ashrrev_i32_e32 v7, 31, v0
	v_lshrrev_b32_e32 v7, 26, v7
	v_add_u32_e32 v8, v0, v7
	v_lshlrev_b32_e32 v9, 3, v6
	v_ashrrev_i32_e32 v7, 6, v8
	v_and_b32_e32 v9, -16, v9
	v_add_u32_e32 v9, v7, v9
	v_and_b32_e32 v10, 3, v7
	v_lshrrev_b32_e32 v11, 2, v9
	s_waitcnt vmcnt(20)
	v_lshlrev_b32_e32 v12, 1, v9
	v_and_b32_e32 v8, 0xc0, v8
	v_and_or_b32 v10, v9, s2, v10
	v_and_b32_e32 v11, 4, v11
	v_and_b32_e32 v12, 24, v12
	v_sub_u32_e32 v0, v0, v8
	s_ashr_i32 s1, s0, 2
	v_or3_b32 v10, v10, v11, v12
	v_lshlrev_b32_e32 v11, 5, v6
	v_ashrrev_i16_sdwa v0, v212, sext(v0) dst_sel:DWORD dst_unused:UNUSED_PAD src0_sel:DWORD src1_sel:BYTE_0
	v_readlane_b32 s2, v253, 39
	v_readlane_b32 s4, v255, 31
	v_and_b32_e32 v11, 32, v11
	v_bfe_i32 v8, v0, 0, 16
	v_readlane_b32 s3, v253, 40
	s_add_u32 s22, s4, s2
	v_readlane_b32 s2, v255, 32
	v_add_lshl_u32 v11, v11, v8, 1
	s_addc_u32 s23, s2, s3
	s_add_i32 s31, s26, 0
	v_lshl_add_u32 v0, v10, 13, v11
	s_add_i32 m0, s31, 0x10000
	v_lshl_add_u32 v134, v9, 13, v11
	v_readlane_b32 s56, v251, 21
	v_mbcnt_lo_u32_b32 v103, -1, 0
	v_mbcnt_hi_u32_b32 v103, -1, v103
	v_lshrrev_b32_e32 v100, 2, v103
	v_and_b32_e32 v100, 7, v100
	v_lshrrev_b32_e32 v101, 3, v103
	v_and_b32_e32 v101, 2, v101
	v_and_b32_e32 v102, 3, v103
	v_xor_b32_e32 v101, v101, v102
	v_lshlrev_b32_e32 v101, 4, v101
	v_lshrrev_b32_e32 v102, 5, v103
	v_lshl_or_b32 v101, v102, 6, v101
	s_lshl_b32 s57, s56, 3
	v_add_u32_e32 v102, s57, v100
	v_lshl_add_u32 v134, v102, 13, v101
	v_add_u32_e32 v132, 0x80000, v134
	v_lshrrev_b32_e32 v102, 2, v100
	v_and_b32_e32 v103, 3, v100
	v_lshl_or_b32 v102, v102, 3, v103
	s_lshr_b32 s57, s56, 2
	s_lshl_b32 s57, s57, 5
	s_and_b32 s58, s56, 1
	s_lshl_b32 s58, s58, 4
	s_or_b32 s57, s57, s58
	s_and_b32 s58, s56, 2
	s_lshl_b32 s58, s58, 1
	s_or_b32 s57, s57, s58
	v_add_u32_e32 v102, s57, v102
	v_lshl_add_u32 v0, v102, 13, v101
	v_add_u32_e32 v130, 0x80000, v0
	global_load_lds_dwordx4 v0, s[22:23]
	s_add_i32 m0, s31, 0x12000
	s_add_u32 s2, s22, 0x100000
	global_load_lds_dwordx4 v130, s[22:23]
	s_addc_u32 s3, s23, 0
	s_add_i32 m0, s31, 0x14000
	s_add_i32 s36, s31, 0x2000
	global_load_lds_dwordx4 v0, s[2:3]
	s_add_i32 m0, s31, 0x16000
	s_add_i32 s37, s31, 0x4000
	global_load_lds_dwordx4 v130, s[2:3]
	v_readlane_b32 s2, v253, 43
	s_mov_b32 m0, s31
	v_readlane_b32 s3, v253, 44
	s_add_i32 s38, s31, 0x6000
	s_cmp_eq_u32 s1, 1
	s_mov_b32 s54, s40
	s_nop 1
	global_load_lds_dwordx4 v134, s[2:3]
	s_mov_b32 m0, s36
	s_nop 0
	global_load_lds_dwordx4 v132, s[2:3]
	v_readlane_b32 s2, v253, 45
	s_mov_b32 m0, s37
	v_readlane_b32 s3, v253, 46
	s_nop 4
	global_load_lds_dwordx4 v134, s[2:3]
	s_mov_b32 m0, s38
	s_nop 0
	global_load_lds_dwordx4 v132, s[2:3]
	s_cselect_b64 s[2:3], -1, 0
	s_cmp_lg_u32 s1, 1
	s_cbranch_scc1 .LBB0_133
	s_barrier
.LBB0_133:
	v_lshl_add_u64 v[10:11], s[22:23], 0, v[0:1]
	v_mov_b32_e32 v131, v1
	v_readlane_b32 s18, v253, 43
	s_lshl_b32 s4, s0, 5
	v_lshl_add_u64 v[12:13], s[22:23], 0, v[130:131]
	v_mov_b32_e32 v135, v1
	v_readlane_b32 s19, v253, 44
	s_and_b32 s6, s4, 0x60
	s_add_i32 m0, s31, 0x18000
	v_lshl_add_u64 v[10:11], v[10:11], 0, s[34:35]
	v_lshl_add_u64 v[14:15], s[18:19], 0, v[134:135]
	v_mov_b32_e32 v133, v1
	s_lshr_b32 s7, s6, 3
	s_waitcnt vmcnt(2)
	s_barrier
	global_load_lds_dwordx4 v[10:11], off
	v_lshl_add_u64 v[10:11], v[12:13], 0, s[34:35]
	s_add_i32 m0, s31, 0x1a000
	s_add_i32 s39, s31, 0x8000
	s_add_i32 s40, s31, 0xa000
	s_waitcnt vmcnt(0)
	v_lshl_add_u64 v[16:17], s[18:19], 0, v[132:133]
	global_load_lds_dwordx4 v[10:11], off
	v_lshl_add_u64 v[10:11], v[14:15], 0, s[34:35]
	s_mov_b32 m0, s39
	s_add_u32 s4, s22, 0x100080
	global_load_lds_dwordx4 v[10:11], off
	v_lshl_add_u64 v[10:11], v[16:17], 0, s[34:35]
	s_mov_b32 m0, s40
	s_addc_u32 s5, s23, 0
	global_load_lds_dwordx4 v[10:11], off
	s_add_i32 m0, s31, 0x1c000
	v_lshl_add_u64 v[10:11], s[4:5], 0, v[0:1]
	global_load_lds_dwordx4 v[10:11], off
	v_lshl_add_u64 v[10:11], s[4:5], 0, v[130:131]
	s_add_i32 m0, s31, 0x1e000
	v_and_b32_e32 v9, 15, v3
	global_load_lds_dwordx4 v[10:11], off
	v_ashrrev_i32_e32 v11, 6, v3
	v_ashrrev_i32_e32 v10, 1, v3
	v_and_b32_e32 v12, 48, v3
	v_lshlrev_b32_e32 v13, 10, v11
	v_lshlrev_b32_e32 v3, 2, v3
	v_lshl_or_b32 v144, s1, 6, v9
	v_lshl_add_u32 v13, s1, 13, v13
	v_lshl_or_b32 v9, v9, 6, v12
	v_and_b32_e32 v3, 32, v3
	v_add_lshl_u32 v11, s7, v11, 10
	v_bitop3_b32 v12, v9, v13, v3 bitop3:0xde
	v_bitop3_b32 v145, v11, v9, v3 bitop3:0xf6
	v_lshlrev_b32_e32 v3, 16, v6
	v_and_b32_e32 v3, 0xfffe0000, v3
	v_lshl_add_u32 v3, v7, 13, v3
	v_and_b32_e32 v6, 1, v6
	v_lshl_or_b32 v3, v6, 6, v3
	v_lshl_add_u32 v136, v8, 1, v3
	v_lshlrev_b32_e32 v3, 16, v2
	v_and_b32_e32 v3, 0xfffe0000, v3
	s_waitcnt vmcnt(6)
	v_lshl_add_u32 v3, v4, 13, v3
	v_and_b32_e32 v2, 1, v2
	v_and_b32_e32 v10, -8, v10
	s_cmp_lt_u32 s0, 4
	v_lshl_or_b32 v2, v2, 6, v3
	v_readlane_b32 s0, v253, 41
	s_cselect_b64 s[4:5], -1, 0
	v_add_u32_e32 v146, s6, v10
	v_mov_b32_e32 v137, v1
	v_lshl_add_u32 v138, v5, 1, v2
	v_mov_b32_e32 v139, v1
	s_mov_b32 s41, 0
	v_add_u32_e32 v147, 0, v12
	v_readlane_b32 s42, v253, 38
	s_mov_b32 s43, s0
	s_barrier
	v_readlane_b32 s1, v253, 42
	v_readlane_b32 s56, v251, 21
	v_mbcnt_lo_u32_b32 v100, -1, 0
	v_mbcnt_hi_u32_b32 v100, -1, v100
	v_and_b32_e32 v101, 15, v100
	v_lshrrev_b32_e32 v102, 4, v100
	v_lshrrev_b32_e32 v103, 1, v101
	v_and_b32_e32 v103, 2, v103
	v_xor_b32_e32 v102, v102, v103
	v_lshlrev_b32_e32 v102, 4, v102
	v_and_b32_e32 v103, 7, v101
	v_lshl_or_b32 v102, v103, 6, v102
	v_lshrrev_b32_e32 v103, 3, v101
	v_lshl_or_b32 v102, v103, 10, v102
	s_lshr_b32 s57, s56, 2
	s_lshl_b32 s57, s57, 13
	v_add_u32_e32 v147, s57, v102
	s_and_b32 s57, s56, 3
	s_lshl_b32 s57, s57, 12
	v_add_u32_e32 v145, s57, v102
	v_mov_b32_e32 v136, v134
	v_mov_b32_e32 v138, v132
	s_branch .LBB0_136

.LBB0_139:
	s_add_u32 s22, s18, 0xfff00080
	s_addc_u32 s23, s19, -1
	s_add_i32 s49, 0, 0x10000
	s_cmp_eq_u32 s48, 60
	s_cselect_b32 s25, s9, s23
	s_cselect_b32 s24, s44, s22
	s_cselect_b32 s23, s7, s47
	s_cselect_b32 s22, s45, s46
	s_add_i32 s52, 0, 0x14000
	v_add_u32_e32 v156, s49, v145
	v_add_u32_e32 v172, s52, v145
	ds_read_b128 v[140:143], v156
	ds_read_b128 v[148:151], v156 offset:512
	ds_read_b128 v[152:155], v156 offset:2048
	ds_read_b128 v[156:159], v156 offset:2560
	ds_read_b128 v[160:163], v172
	ds_read_b128 v[164:167], v172 offset:512
	ds_read_b128 v[168:171], v172 offset:2048
	ds_read_b128 v[190:193], v172 offset:2560
	v_lshl_add_u64 v[172:173], s[18:19], 0, v[136:137]
	s_add_i32 m0, s31, 0xc000
	ds_read_b128 v[194:197], v147
	ds_read_b128 v[198:201], v147 offset:512
	ds_read_b128 v[202:205], v147 offset:2048
	ds_read_b128 v[206:209], v147 offset:2560
	ds_read_b128 v[228:231], v147 offset:4096
	ds_read_b128 v[232:235], v147 offset:4608
	ds_read_b128 v[236:239], v147 offset:6144
	ds_read_b128 v[240:243], v147 offset:6656
	global_load_lds_dwordx4 v[172:173], off
	v_lshl_add_u64 v[172:173], s[18:19], 0, v[138:139]
	s_add_i32 m0, s31, 0xe000
	s_nop 0
	global_load_lds_dwordx4 v[172:173], off
	s_waitcnt vmcnt(8)
	s_waitcnt lgkmcnt(0)
	s_barrier
	s_setprio 1
	s_waitcnt lgkmcnt(0)
	v_mfma_f32_16x16x32_bf16 v[126:129], v[140:143], v[194:197], v[126:129]
	v_mfma_f32_16x16x32_bf16 v[126:129], v[148:151], v[198:201], v[126:129]
	v_mfma_f32_16x16x32_bf16 v[118:121], v[148:151], v[206:209], v[118:121]
	v_mfma_f32_16x16x32_bf16 v[118:121], v[140:143], v[202:205], v[118:121]
	v_mfma_f32_16x16x32_bf16 v[102:105], v[140:143], v[228:231], v[102:105]
	v_mfma_f32_16x16x32_bf16 v[102:105], v[148:151], v[232:235], v[102:105]
	v_mfma_f32_16x16x32_bf16 v[86:89], v[148:151], v[240:243], v[86:89]
	v_mfma_f32_16x16x32_bf16 v[86:89], v[140:143], v[236:239], v[86:89]
	v_mfma_f32_16x16x32_bf16 v[78:81], v[152:155], v[236:239], v[78:81]
	v_mfma_f32_16x16x32_bf16 v[78:81], v[156:159], v[240:243], v[78:81]
	v_mfma_f32_16x16x32_bf16 v[94:97], v[156:159], v[232:235], v[94:97]
	v_mfma_f32_16x16x32_bf16 v[94:97], v[152:155], v[228:231], v[94:97]
	v_mfma_f32_16x16x32_bf16 v[110:113], v[152:155], v[202:205], v[110:113]
	v_mfma_f32_16x16x32_bf16 v[110:113], v[156:159], v[206:209], v[110:113]
	v_mfma_f32_16x16x32_bf16 v[122:125], v[156:159], v[198:201], v[122:125]
	v_mfma_f32_16x16x32_bf16 v[122:125], v[152:155], v[194:197], v[122:125]
	s_setprio 0
	s_setprio 1
	v_mfma_f32_16x16x32_bf16 v[114:117], v[160:163], v[194:197], v[114:117]
	v_mfma_f32_16x16x32_bf16 v[114:117], v[164:167], v[198:201], v[114:117]
	v_mfma_f32_16x16x32_bf16 v[98:101], v[164:167], v[206:209], v[98:101]
	v_mfma_f32_16x16x32_bf16 v[98:101], v[160:163], v[202:205], v[98:101]
	v_mfma_f32_16x16x32_bf16 v[82:85], v[160:163], v[228:231], v[82:85]
	v_mfma_f32_16x16x32_bf16 v[82:85], v[164:167], v[232:235], v[82:85]
	v_mfma_f32_16x16x32_bf16 v[70:73], v[164:167], v[240:243], v[70:73]
	v_mfma_f32_16x16x32_bf16 v[70:73], v[160:163], v[236:239], v[70:73]
	v_mfma_f32_16x16x32_bf16 v[66:69], v[168:171], v[236:239], v[66:69]
	v_mfma_f32_16x16x32_bf16 v[66:69], v[190:193], v[240:243], v[66:69]
	v_mfma_f32_16x16x32_bf16 v[74:77], v[190:193], v[232:235], v[74:77]
	v_mfma_f32_16x16x32_bf16 v[74:77], v[168:171], v[228:231], v[74:77]
	v_mfma_f32_16x16x32_bf16 v[90:93], v[168:171], v[202:205], v[90:93]
	v_mfma_f32_16x16x32_bf16 v[90:93], v[190:193], v[206:209], v[90:93]
	v_mfma_f32_16x16x32_bf16 v[106:109], v[190:193], v[198:201], v[106:109]
	v_mfma_f32_16x16x32_bf16 v[106:109], v[168:171], v[194:197], v[106:109]
	s_setprio 0
	s_barrier
	s_add_i32 s49, s49, s26
	v_lshl_add_u64 v[172:173], s[22:23], 0, v[0:1]
	s_mov_b32 m0, s49
	ds_read_b128 v[194:197], v147 offset:16384
	ds_read_b128 v[198:201], v147 offset:16896
	ds_read_b128 v[202:205], v147 offset:18432
	ds_read_b128 v[206:209], v147 offset:18944
	ds_read_b128 v[228:231], v147 offset:20480
	ds_read_b128 v[232:235], v147 offset:20992
	ds_read_b128 v[236:239], v147 offset:22528
	ds_read_b128 v[240:243], v147 offset:23040
	global_load_lds_dwordx4 v[172:173], off
	s_add_i32 m0, s49, 0x2000
	s_add_u32 s50, s22, 0x100000
	v_lshl_add_u64 v[178:179], s[22:23], 0, v[130:131]
	s_addc_u32 s51, s23, 0
	s_add_i32 s49, s52, s26
	global_load_lds_dwordx4 v[178:179], off
	v_lshl_add_u64 v[180:181], s[50:51], 0, v[0:1]
	s_mov_b32 m0, s49
	v_lshl_add_u64 v[210:211], s[24:25], 0, v[132:133]
	global_load_lds_dwordx4 v[180:181], off
	v_lshl_add_u64 v[180:181], s[50:51], 0, v[130:131]
	s_add_i32 m0, s49, 0x2000
	s_nop 0
	global_load_lds_dwordx4 v[180:181], off
	v_lshl_add_u64 v[180:181], s[24:25], 0, v[134:135]
	s_mov_b32 m0, s31
	s_nop 0
	global_load_lds_dwordx4 v[180:181], off
	s_mov_b32 m0, s36
	s_nop 0
	global_load_lds_dwordx4 v[210:211], off
	s_waitcnt vmcnt(8)
	s_waitcnt lgkmcnt(0)
	s_barrier
	s_setprio 1
	s_waitcnt lgkmcnt(0)
	v_mfma_f32_16x16x32_bf16 v[62:65], v[140:143], v[194:197], v[62:65]
	v_mfma_f32_16x16x32_bf16 v[62:65], v[148:151], v[198:201], v[62:65]
	v_mfma_f32_16x16x32_bf16 v[54:57], v[148:151], v[206:209], v[54:57]
	v_mfma_f32_16x16x32_bf16 v[54:57], v[140:143], v[202:205], v[54:57]
	v_mfma_f32_16x16x32_bf16 v[38:41], v[140:143], v[228:231], v[38:41]
	v_mfma_f32_16x16x32_bf16 v[38:41], v[148:151], v[232:235], v[38:41]
	v_mfma_f32_16x16x32_bf16 v[22:25], v[148:151], v[240:243], v[22:25]
	v_mfma_f32_16x16x32_bf16 v[22:25], v[140:143], v[236:239], v[22:25]
	v_mfma_f32_16x16x32_bf16 v[14:17], v[152:155], v[236:239], v[14:17]
	v_mfma_f32_16x16x32_bf16 v[14:17], v[156:159], v[240:243], v[14:17]
	v_mfma_f32_16x16x32_bf16 v[30:33], v[156:159], v[232:235], v[30:33]
	v_mfma_f32_16x16x32_bf16 v[30:33], v[152:155], v[228:231], v[30:33]
	v_mfma_f32_16x16x32_bf16 v[46:49], v[152:155], v[202:205], v[46:49]
	v_mfma_f32_16x16x32_bf16 v[46:49], v[156:159], v[206:209], v[46:49]
	v_mfma_f32_16x16x32_bf16 v[58:61], v[156:159], v[198:201], v[58:61]
	v_mfma_f32_16x16x32_bf16 v[58:61], v[152:155], v[194:197], v[58:61]
	s_setprio 0
	s_setprio 1
	v_mfma_f32_16x16x32_bf16 v[50:53], v[160:163], v[194:197], v[50:53]
	v_mfma_f32_16x16x32_bf16 v[50:53], v[164:167], v[198:201], v[50:53]
	v_mfma_f32_16x16x32_bf16 v[34:37], v[164:167], v[206:209], v[34:37]
	v_mfma_f32_16x16x32_bf16 v[34:37], v[160:163], v[202:205], v[34:37]
	v_mfma_f32_16x16x32_bf16 v[18:21], v[160:163], v[228:231], v[18:21]
	v_mfma_f32_16x16x32_bf16 v[18:21], v[164:167], v[232:235], v[18:21]
	v_mfma_f32_16x16x32_bf16 v[6:9], v[164:167], v[240:243], v[6:9]
	v_mfma_f32_16x16x32_bf16 v[6:9], v[160:163], v[236:239], v[6:9]
	v_mfma_f32_16x16x32_bf16 v[2:5], v[168:171], v[236:239], v[2:5]
	v_mfma_f32_16x16x32_bf16 v[2:5], v[190:193], v[240:243], v[2:5]
	v_mfma_f32_16x16x32_bf16 v[10:13], v[190:193], v[232:235], v[10:13]
	v_mfma_f32_16x16x32_bf16 v[10:13], v[168:171], v[228:231], v[10:13]
	v_mfma_f32_16x16x32_bf16 v[26:29], v[168:171], v[202:205], v[26:29]
	v_mfma_f32_16x16x32_bf16 v[26:29], v[190:193], v[206:209], v[26:29]
	v_mfma_f32_16x16x32_bf16 v[42:45], v[190:193], v[198:201], v[42:45]
	v_mfma_f32_16x16x32_bf16 v[42:45], v[168:171], v[194:197], v[42:45]
	s_setprio 0
	s_barrier
	s_add_i32 s49, 0, 0x18000
	s_add_i32 s50, 0, 0x1c000
	v_add_u32_e32 v156, s49, v145
	v_add_u32_e32 v175, s50, v145
	ds_read_b128 v[140:143], v156
	ds_read_b128 v[148:151], v156 offset:512
	ds_read_b128 v[152:155], v156 offset:2048
	ds_read_b128 v[156:159], v156 offset:2560
	ds_read_b128 v[160:163], v175
	ds_read_b128 v[164:167], v175 offset:512
	ds_read_b128 v[168:171], v175 offset:2048
	ds_read_b128 v[190:193], v175 offset:2560
	s_add_u32 s24, s24, 0x100000
	s_addc_u32 s25, s25, 0
	s_mov_b32 m0, s37
	v_lshl_add_u64 v[244:245], s[24:25], 0, v[134:135]
	ds_read_b128 v[194:197], v147 offset:32768
	ds_read_b128 v[198:201], v147 offset:33280
	ds_read_b128 v[202:205], v147 offset:34816
	ds_read_b128 v[206:209], v147 offset:35328
	ds_read_b128 v[228:231], v147 offset:36864
	ds_read_b128 v[232:235], v147 offset:37376
	ds_read_b128 v[236:239], v147 offset:38912
	ds_read_b128 v[240:243], v147 offset:39424
	global_load_lds_dwordx4 v[244:245], off
	v_lshl_add_u64 v[244:245], s[24:25], 0, v[132:133]
	s_mov_b32 m0, s38
	s_nop 0
	global_load_lds_dwordx4 v[244:245], off
	s_waitcnt vmcnt(8)
	s_waitcnt lgkmcnt(0)
	s_barrier
	s_setprio 1
	s_waitcnt lgkmcnt(0)
	v_mfma_f32_16x16x32_bf16 v[126:129], v[140:143], v[194:197], v[126:129]
	v_mfma_f32_16x16x32_bf16 v[126:129], v[148:151], v[198:201], v[126:129]
	v_mfma_f32_16x16x32_bf16 v[118:121], v[148:151], v[206:209], v[118:121]
	v_mfma_f32_16x16x32_bf16 v[118:121], v[140:143], v[202:205], v[118:121]
	v_mfma_f32_16x16x32_bf16 v[102:105], v[140:143], v[228:231], v[102:105]
	v_mfma_f32_16x16x32_bf16 v[102:105], v[148:151], v[232:235], v[102:105]
	v_mfma_f32_16x16x32_bf16 v[86:89], v[148:151], v[240:243], v[86:89]
	v_mfma_f32_16x16x32_bf16 v[86:89], v[140:143], v[236:239], v[86:89]
	v_mfma_f32_16x16x32_bf16 v[78:81], v[152:155], v[236:239], v[78:81]
	v_mfma_f32_16x16x32_bf16 v[78:81], v[156:159], v[240:243], v[78:81]
	v_mfma_f32_16x16x32_bf16 v[94:97], v[156:159], v[232:235], v[94:97]
	v_mfma_f32_16x16x32_bf16 v[94:97], v[152:155], v[228:231], v[94:97]
	v_mfma_f32_16x16x32_bf16 v[110:113], v[152:155], v[202:205], v[110:113]
	v_mfma_f32_16x16x32_bf16 v[110:113], v[156:159], v[206:209], v[110:113]
	v_mfma_f32_16x16x32_bf16 v[122:125], v[156:159], v[198:201], v[122:125]
	v_mfma_f32_16x16x32_bf16 v[122:125], v[152:155], v[194:197], v[122:125]
	s_setprio 0
	s_setprio 1
	v_mfma_f32_16x16x32_bf16 v[114:117], v[160:163], v[194:197], v[114:117]
	v_mfma_f32_16x16x32_bf16 v[114:117], v[164:167], v[198:201], v[114:117]
	v_mfma_f32_16x16x32_bf16 v[98:101], v[164:167], v[206:209], v[98:101]
	v_mfma_f32_16x16x32_bf16 v[98:101], v[160:163], v[202:205], v[98:101]
	v_mfma_f32_16x16x32_bf16 v[82:85], v[160:163], v[228:231], v[82:85]
	v_mfma_f32_16x16x32_bf16 v[82:85], v[164:167], v[232:235], v[82:85]
	v_mfma_f32_16x16x32_bf16 v[70:73], v[164:167], v[240:243], v[70:73]
	v_mfma_f32_16x16x32_bf16 v[70:73], v[160:163], v[236:239], v[70:73]
	v_mfma_f32_16x16x32_bf16 v[66:69], v[168:171], v[236:239], v[66:69]
	v_mfma_f32_16x16x32_bf16 v[66:69], v[190:193], v[240:243], v[66:69]
	v_mfma_f32_16x16x32_bf16 v[74:77], v[190:193], v[232:235], v[74:77]
	v_mfma_f32_16x16x32_bf16 v[74:77], v[168:171], v[228:231], v[74:77]
	v_mfma_f32_16x16x32_bf16 v[90:93], v[168:171], v[202:205], v[90:93]
	v_mfma_f32_16x16x32_bf16 v[90:93], v[190:193], v[206:209], v[90:93]
	v_mfma_f32_16x16x32_bf16 v[106:109], v[190:193], v[198:201], v[106:109]
	v_mfma_f32_16x16x32_bf16 v[106:109], v[168:171], v[194:197], v[106:109]
	s_setprio 0
	s_barrier
	s_add_i32 s24, s49, s26
	v_lshl_add_u64 v[172:173], v[172:173], 0, s[34:35]
	s_mov_b32 m0, s24
	ds_read_b128 v[194:197], v147 offset:49152
	ds_read_b128 v[198:201], v147 offset:49664
	ds_read_b128 v[202:205], v147 offset:51200
	ds_read_b128 v[206:209], v147 offset:51712
	ds_read_b128 v[228:231], v147 offset:53248
	ds_read_b128 v[232:235], v147 offset:53760
	ds_read_b128 v[236:239], v147 offset:55296
	ds_read_b128 v[240:243], v147 offset:55808
	global_load_lds_dwordx4 v[172:173], off
	s_add_i32 m0, s24, 0x2000
	s_add_u32 s22, s22, 0x100080
	v_lshl_add_u64 v[172:173], v[178:179], 0, s[34:35]
	s_addc_u32 s23, s23, 0
	s_add_i32 s24, s50, s26
	global_load_lds_dwordx4 v[172:173], off
	v_lshl_add_u64 v[172:173], s[22:23], 0, v[0:1]
	s_mov_b32 m0, s24
	s_nop 0
	global_load_lds_dwordx4 v[172:173], off
	v_lshl_add_u64 v[172:173], s[22:23], 0, v[130:131]
	s_add_i32 m0, s24, 0x2000
	s_nop 0
	global_load_lds_dwordx4 v[172:173], off
	v_lshl_add_u64 v[172:173], v[180:181], 0, s[34:35]
	s_mov_b32 m0, s39
	s_nop 0
	global_load_lds_dwordx4 v[172:173], off
	v_lshl_add_u64 v[172:173], v[210:211], 0, s[34:35]
	s_mov_b32 m0, s40
	s_nop 0
	global_load_lds_dwordx4 v[172:173], off
	s_waitcnt vmcnt(8)
	s_waitcnt lgkmcnt(0)
	s_barrier
	s_setprio 1
	s_waitcnt lgkmcnt(0)
	v_mfma_f32_16x16x32_bf16 v[62:65], v[140:143], v[194:197], v[62:65]
	v_mfma_f32_16x16x32_bf16 v[62:65], v[148:151], v[198:201], v[62:65]
	v_mfma_f32_16x16x32_bf16 v[54:57], v[148:151], v[206:209], v[54:57]
	v_mfma_f32_16x16x32_bf16 v[54:57], v[140:143], v[202:205], v[54:57]
	v_mfma_f32_16x16x32_bf16 v[38:41], v[140:143], v[228:231], v[38:41]
	v_mfma_f32_16x16x32_bf16 v[38:41], v[148:151], v[232:235], v[38:41]
	v_mfma_f32_16x16x32_bf16 v[22:25], v[148:151], v[240:243], v[22:25]
	v_mfma_f32_16x16x32_bf16 v[22:25], v[140:143], v[236:239], v[22:25]
	v_mfma_f32_16x16x32_bf16 v[14:17], v[152:155], v[236:239], v[14:17]
	v_mfma_f32_16x16x32_bf16 v[14:17], v[156:159], v[240:243], v[14:17]
	v_mfma_f32_16x16x32_bf16 v[30:33], v[156:159], v[232:235], v[30:33]
	v_mfma_f32_16x16x32_bf16 v[30:33], v[152:155], v[228:231], v[30:33]
	v_mfma_f32_16x16x32_bf16 v[46:49], v[152:155], v[202:205], v[46:49]
	v_mfma_f32_16x16x32_bf16 v[46:49], v[156:159], v[206:209], v[46:49]
	v_mfma_f32_16x16x32_bf16 v[58:61], v[156:159], v[198:201], v[58:61]
	v_mfma_f32_16x16x32_bf16 v[58:61], v[152:155], v[194:197], v[58:61]
	s_setprio 0
	s_setprio 1
	v_mfma_f32_16x16x32_bf16 v[50:53], v[160:163], v[194:197], v[50:53]
	v_mfma_f32_16x16x32_bf16 v[50:53], v[164:167], v[198:201], v[50:53]
	v_mfma_f32_16x16x32_bf16 v[34:37], v[164:167], v[206:209], v[34:37]
	v_mfma_f32_16x16x32_bf16 v[34:37], v[160:163], v[202:205], v[34:37]
	v_mfma_f32_16x16x32_bf16 v[18:21], v[160:163], v[228:231], v[18:21]
	v_mfma_f32_16x16x32_bf16 v[18:21], v[164:167], v[232:235], v[18:21]
	v_mfma_f32_16x16x32_bf16 v[6:9], v[164:167], v[240:243], v[6:9]
	v_mfma_f32_16x16x32_bf16 v[6:9], v[160:163], v[236:239], v[6:9]
	v_mfma_f32_16x16x32_bf16 v[2:5], v[168:171], v[236:239], v[2:5]
	v_mfma_f32_16x16x32_bf16 v[2:5], v[190:193], v[240:243], v[2:5]
	v_mfma_f32_16x16x32_bf16 v[10:13], v[190:193], v[232:235], v[10:13]
	v_mfma_f32_16x16x32_bf16 v[10:13], v[168:171], v[228:231], v[10:13]
	v_mfma_f32_16x16x32_bf16 v[26:29], v[168:171], v[202:205], v[26:29]
	v_mfma_f32_16x16x32_bf16 v[26:29], v[190:193], v[206:209], v[26:29]
	v_mfma_f32_16x16x32_bf16 v[42:45], v[190:193], v[198:201], v[42:45]
	v_mfma_f32_16x16x32_bf16 v[42:45], v[168:171], v[194:197], v[42:45]
	s_setprio 0
	s_barrier
	s_add_i32 s48, s48, 2
	s_add_u32 s18, s18, 0x100
	s_addc_u32 s19, s19, 0
	s_add_u32 s46, s46, 0x100
	s_addc_u32 s47, s47, 0
	s_cmp_gt_u32 s48, 61
	s_cbranch_scc0 .LBB0_139
	s_and_b64 vcc, exec, s[4:5]
	s_cbranch_vccz .LBB0_142
	s_barrier

.LBB0_561:
	s_andn2_b64 vcc, exec, s[0:1]
	v_readlane_b32 s0, v253, 15
	v_readlane_b32 s1, v253, 16
	s_nop 1
	v_cndmask_b32_e64 v0, 0, 1, s[0:1]
	v_cmp_ne_u32_e64 s[36:37], 1, v0
	s_cbranch_vccnz .LBB0_634
	v_readlane_b32 s0, v251, 21
	s_and_b64 vcc, exec, s[36:37]
	s_waitcnt vmcnt(0)
	v_mbcnt_lo_u32_b32 v3, -1, 0
	v_mbcnt_hi_u32_b32 v3, -1, v3
	s_cbranch_vccnz .LBB0_582
	v_readlane_b32 s1, v255, 31
	s_add_u32 s26, s1, 0x5200000
	v_readlane_b32 s1, v255, 32
	s_addc_u32 s31, s1, 0
	s_lshl_b32 s38, s0, 10
	v_lshl_add_u32 v0, v3, 4, s38
	s_waitcnt vmcnt(0)
	v_add_u32_e32 v4, 0x2000, v0
	v_ashrrev_i32_e32 v2, 31, v4
	v_lshrrev_b32_e32 v2, 22, v2
	v_add_u32_e32 v2, v4, v2
	v_ashrrev_i32_e32 v2, 10, v2
	v_mul_i32_i24_e32 v5, 0x400, v2
	v_sub_u32_e32 v4, v4, v5
	v_lshrrev_b32_e32 v5, 4, v4
	v_bitop3_b32 v5, v5, v4, 32 bitop3:0x6c
	v_ashrrev_i32_e32 v4, 31, v5
	v_lshrrev_b32_e32 v4, 26, v4
	v_add_u32_e32 v6, v5, v4
	v_ashrrev_i32_e32 v4, 6, v6
	v_lshlrev_b32_e32 v7, 3, v2
	v_and_b32_e32 v6, 0xffc0, v6
	v_and_b32_e32 v7, -16, v7
	v_sub_u32_e32 v5, v5, v6
	v_add_u32_e32 v7, v4, v7
	v_lshrrev_b16_e32 v6, 7, v5
	v_and_b32_e32 v8, 3, v4
	s_mov_b32 s2, 0x7ffe0
	v_lshrrev_b32_e32 v9, 2, v7
	v_lshlrev_b32_e32 v10, 1, v7
	v_and_b32_e32 v6, 1, v6
	v_and_or_b32 v8, v7, s2, v8
	v_and_b32_e32 v9, 4, v9
	v_and_b32_e32 v10, 24, v10
	v_add_u16_e32 v5, v5, v6
	v_or3_b32 v8, v8, v9, v10
	v_lshlrev_b32_e32 v9, 5, v2
	v_ashrrev_i16_sdwa v5, v212, sext(v5) dst_sel:DWORD dst_unused:UNUSED_PAD src0_sel:DWORD src1_sel:BYTE_0
	v_and_b32_e32 v9, 32, v9
	v_bfe_i32 v5, v5, 0, 16
	v_add_lshl_u32 v6, v9, v5, 1
	v_lshl_add_u32 v130, v8, 13, v6
	v_lshl_add_u32 v132, v7, 13, v6
	v_ashrrev_i32_e32 v6, 31, v0
	v_lshrrev_b32_e32 v6, 22, v6
	v_add_u32_e32 v6, v0, v6
	v_ashrrev_i32_e32 v6, 10, v6
	v_mul_i32_i24_e32 v7, 0x400, v6
	v_sub_u32_e32 v0, v0, v7
	v_lshrrev_b32_e32 v7, 4, v0
	v_bitop3_b32 v0, v7, v0, 32 bitop3:0x6c
	v_ashrrev_i32_e32 v7, 31, v0
	v_lshrrev_b32_e32 v7, 26, v7
	v_add_u32_e32 v8, v0, v7
	v_lshlrev_b32_e32 v9, 3, v6
	v_ashrrev_i32_e32 v7, 6, v8
	v_and_b32_e32 v9, -16, v9
	v_add_u32_e32 v9, v7, v9
	v_and_b32_e32 v10, 3, v7
	v_lshrrev_b32_e32 v11, 2, v9
	v_lshlrev_b32_e32 v12, 1, v9
	v_and_b32_e32 v8, 0xc0, v8
	v_and_or_b32 v10, v9, s2, v10
	v_and_b32_e32 v11, 4, v11
	v_and_b32_e32 v12, 24, v12
	v_sub_u32_e32 v0, v0, v8
	s_ashr_i32 s1, s0, 2
	v_or3_b32 v10, v10, v11, v12
	v_lshlrev_b32_e32 v11, 5, v6
	v_ashrrev_i16_sdwa v0, v212, sext(v0) dst_sel:DWORD dst_unused:UNUSED_PAD src0_sel:DWORD src1_sel:BYTE_0
	v_readlane_b32 s2, v254, 13
	v_and_b32_e32 v11, 32, v11
	v_bfe_i32 v8, v0, 0, 16
	v_readlane_b32 s3, v254, 14
	s_add_u32 s22, s26, s2
	v_add_lshl_u32 v11, v11, v8, 1
	s_addc_u32 s23, s31, s3
	s_add_i32 s39, s38, 0
	v_lshl_add_u32 v0, v10, 13, v11
	s_add_i32 m0, s39, 0x10000
	v_lshl_add_u32 v134, v9, 13, v11
	v_readlane_b32 s56, v251, 21
	v_mbcnt_lo_u32_b32 v103, -1, 0
	v_mbcnt_hi_u32_b32 v103, -1, v103
	v_lshrrev_b32_e32 v100, 2, v103
	v_and_b32_e32 v100, 7, v100
	v_lshrrev_b32_e32 v101, 3, v103
	v_and_b32_e32 v101, 2, v101
	v_and_b32_e32 v102, 3, v103
	v_xor_b32_e32 v101, v101, v102
	v_lshlrev_b32_e32 v101, 4, v101
	v_lshrrev_b32_e32 v102, 5, v103
	v_lshl_or_b32 v101, v102, 6, v101
	s_lshl_b32 s57, s56, 3
	v_add_u32_e32 v102, s57, v100
	v_lshl_add_u32 v134, v102, 13, v101
	v_add_u32_e32 v132, 0x80000, v134
	v_lshrrev_b32_e32 v102, 2, v100
	v_and_b32_e32 v103, 3, v100
	v_lshl_or_b32 v102, v102, 3, v103
	s_lshr_b32 s57, s56, 2
	s_lshl_b32 s57, s57, 5
	s_and_b32 s58, s56, 1
	s_lshl_b32 s58, s58, 4
	s_or_b32 s57, s57, s58
	s_and_b32 s58, s56, 2
	s_lshl_b32 s58, s58, 1
	s_or_b32 s57, s57, s58
	v_add_u32_e32 v102, s57, v102
	v_lshl_add_u32 v0, v102, 13, v101
	v_add_u32_e32 v130, 0x80000, v0
	global_load_lds_dwordx4 v0, s[22:23]
	s_add_i32 m0, s39, 0x12000
	s_add_u32 s2, s22, 0x100000
	global_load_lds_dwordx4 v130, s[22:23]
	s_addc_u32 s3, s23, 0
	s_add_i32 m0, s39, 0x14000
	s_add_i32 s40, s39, 0x2000
	global_load_lds_dwordx4 v0, s[2:3]
	s_add_i32 m0, s39, 0x16000
	s_add_i32 s41, s39, 0x4000
	global_load_lds_dwordx4 v130, s[2:3]
	v_readlane_b32 s2, v254, 17
	s_mov_b32 m0, s39
	v_readlane_b32 s3, v254, 18
	s_add_i32 s42, s39, 0x6000
	s_cmp_eq_u32 s1, 1
	s_nop 2
	global_load_lds_dwordx4 v134, s[2:3]
	s_mov_b32 m0, s40
	s_nop 0
	global_load_lds_dwordx4 v132, s[2:3]
	v_readlane_b32 s2, v254, 19
	s_mov_b32 m0, s41
	v_readlane_b32 s3, v254, 20
	s_nop 4
	global_load_lds_dwordx4 v134, s[2:3]
	s_mov_b32 m0, s42
	s_nop 0
	global_load_lds_dwordx4 v132, s[2:3]
	s_cselect_b64 s[2:3], -1, 0
	s_cmp_lg_u32 s1, 1
	s_cbranch_scc1 .LBB0_565
	s_barrier
.LBB0_565:
	v_lshl_add_u64 v[10:11], s[22:23], 0, v[0:1]
	v_mov_b32_e32 v131, v1
	v_readlane_b32 s18, v254, 17
	s_lshl_b32 s4, s0, 5
	v_lshl_add_u64 v[12:13], s[22:23], 0, v[130:131]
	v_mov_b32_e32 v135, v1
	v_readlane_b32 s19, v254, 18
	s_and_b32 s6, s4, 0x60
	s_add_i32 m0, s39, 0x18000
	v_lshl_add_u64 v[10:11], v[10:11], 0, s[34:35]
	v_lshl_add_u64 v[14:15], s[18:19], 0, v[134:135]
	v_mov_b32_e32 v133, v1
	s_lshr_b32 s7, s6, 3
	s_waitcnt vmcnt(2)
	s_barrier
	global_load_lds_dwordx4 v[10:11], off
	v_lshl_add_u64 v[10:11], v[12:13], 0, s[34:35]
	s_add_i32 m0, s39, 0x1a000
	s_add_i32 s43, s39, 0x8000
	s_add_i32 s44, s39, 0xa000
	v_lshl_add_u64 v[16:17], s[18:19], 0, v[132:133]
	global_load_lds_dwordx4 v[10:11], off
	v_lshl_add_u64 v[10:11], v[14:15], 0, s[34:35]
	s_mov_b32 m0, s43
	s_add_u32 s4, s22, 0x100080
	global_load_lds_dwordx4 v[10:11], off
	v_lshl_add_u64 v[10:11], v[16:17], 0, s[34:35]
	s_mov_b32 m0, s44
	s_addc_u32 s5, s23, 0
	global_load_lds_dwordx4 v[10:11], off
	s_add_i32 m0, s39, 0x1c000
	v_lshl_add_u64 v[10:11], s[4:5], 0, v[0:1]
	global_load_lds_dwordx4 v[10:11], off
	v_lshl_add_u64 v[10:11], s[4:5], 0, v[130:131]
	s_add_i32 m0, s39, 0x1e000
	v_and_b32_e32 v9, 15, v3
	global_load_lds_dwordx4 v[10:11], off
	v_ashrrev_i32_e32 v11, 6, v3
	v_ashrrev_i32_e32 v10, 1, v3
	v_and_b32_e32 v12, 48, v3
	v_lshlrev_b32_e32 v13, 10, v11
	v_lshlrev_b32_e32 v3, 2, v3
	v_lshl_or_b32 v142, s1, 6, v9
	v_lshl_add_u32 v13, s1, 13, v13
	v_lshl_or_b32 v9, v9, 6, v12
	v_and_b32_e32 v3, 32, v3
	v_add_lshl_u32 v11, s7, v11, 10
	v_bitop3_b32 v12, v9, v13, v3 bitop3:0xde
	v_bitop3_b32 v143, v11, v9, v3 bitop3:0xf6
	v_lshlrev_b32_e32 v3, 16, v6
	v_and_b32_e32 v3, 0xfffe0000, v3
	v_lshl_add_u32 v3, v7, 13, v3
	v_and_b32_e32 v6, 1, v6
	v_lshl_or_b32 v3, v6, 6, v3
	v_lshl_add_u32 v136, v8, 1, v3
	v_lshlrev_b32_e32 v3, 16, v2
	v_and_b32_e32 v3, 0xfffe0000, v3
	s_waitcnt vmcnt(6)
	v_lshl_add_u32 v3, v4, 13, v3
	v_and_b32_e32 v2, 1, v2
	v_and_b32_e32 v10, -8, v10
	s_cmp_lt_u32 s0, 4
	v_lshl_or_b32 v2, v2, 6, v3
	v_readlane_b32 s0, v254, 30
	s_cselect_b64 s[4:5], -1, 0
	v_add_u32_e32 v144, s6, v10
	v_mov_b32_e32 v137, v1
	v_lshl_add_u32 v138, v5, 1, v2
	v_mov_b32_e32 v139, v1
	s_mov_b32 s45, 0
	v_add_u32_e32 v145, 0, v12
	v_readlane_b32 s46, v254, 12
	s_mov_b32 s47, s0
	s_barrier
	v_readlane_b32 s1, v254, 31
	v_readlane_b32 s56, v251, 21
	v_mbcnt_lo_u32_b32 v100, -1, 0
	v_mbcnt_hi_u32_b32 v100, -1, v100
	v_and_b32_e32 v101, 15, v100
	v_lshrrev_b32_e32 v102, 4, v100
	v_lshrrev_b32_e32 v103, 1, v101
	v_and_b32_e32 v103, 2, v103
	v_xor_b32_e32 v102, v102, v103
	v_lshlrev_b32_e32 v102, 4, v102
	v_and_b32_e32 v103, 7, v101
	v_lshl_or_b32 v102, v103, 6, v102
	v_lshrrev_b32_e32 v103, 3, v101
	v_lshl_or_b32 v102, v103, 10, v102
	s_lshr_b32 s57, s56, 2
	s_lshl_b32 s57, s57, 13
	v_add_u32_e32 v145, s57, v102
	s_and_b32 s57, s56, 3
	s_lshl_b32 s57, s57, 12
	v_add_u32_e32 v143, s57, v102
	v_mov_b32_e32 v136, v134
	v_mov_b32_e32 v138, v132
	s_branch .LBB0_568

.LBB0_575:
	s_add_u32 s22, s18, 0xfff00080
	s_addc_u32 s23, s19, -1
	s_add_i32 s53, 0, 0x10000
	s_cmp_eq_u32 s52, 60
	s_cselect_b32 s25, s9, s23
	s_cselect_b32 s24, s48, s22
	v_add_u32_e32 v140, s53, v143
	s_cselect_b32 s23, s7, s51
	s_cselect_b32 s22, s49, s50
	s_add_i32 s56, 0, 0x14000
	ds_read_b128 v[146:149], v140
	ds_read_b128 v[150:153], v140 offset:512
	ds_read_b128 v[154:157], v140 offset:2048
	ds_read_b128 v[158:161], v140 offset:2560
	v_add_u32_e32 v140, s56, v143
	ds_read_b128 v[162:165], v140
	ds_read_b128 v[166:169], v140 offset:512
	ds_read_b128 v[170:173], v140 offset:2048
	ds_read_b128 v[178:181], v140 offset:2560
	v_lshl_add_u64 v[140:141], s[18:19], 0, v[136:137]
	s_add_i32 m0, s39, 0xc000
	ds_read_b128 v[190:193], v145
	ds_read_b128 v[194:197], v145 offset:512
	ds_read_b128 v[198:201], v145 offset:2048
	ds_read_b128 v[202:205], v145 offset:2560
	ds_read_b128 v[206:209], v145 offset:4096
	ds_read_b128 v[228:231], v145 offset:4608
	ds_read_b128 v[232:235], v145 offset:6144
	ds_read_b128 v[236:239], v145 offset:6656
	global_load_lds_dwordx4 v[140:141], off
	v_lshl_add_u64 v[140:141], s[18:19], 0, v[138:139]
	s_add_i32 m0, s39, 0xe000
	s_nop 0
	global_load_lds_dwordx4 v[140:141], off
	s_waitcnt vmcnt(8)
	s_waitcnt lgkmcnt(0)
	s_barrier
	s_setprio 1
	s_waitcnt lgkmcnt(0)
	v_mfma_f32_16x16x32_bf16 v[126:129], v[146:149], v[190:193], v[126:129]
	v_mfma_f32_16x16x32_bf16 v[126:129], v[150:153], v[194:197], v[126:129]
	v_mfma_f32_16x16x32_bf16 v[118:121], v[150:153], v[202:205], v[118:121]
	v_mfma_f32_16x16x32_bf16 v[118:121], v[146:149], v[198:201], v[118:121]
	v_mfma_f32_16x16x32_bf16 v[102:105], v[146:149], v[206:209], v[102:105]
	v_mfma_f32_16x16x32_bf16 v[102:105], v[150:153], v[228:231], v[102:105]
	v_mfma_f32_16x16x32_bf16 v[86:89], v[150:153], v[236:239], v[86:89]
	v_mfma_f32_16x16x32_bf16 v[86:89], v[146:149], v[232:235], v[86:89]
	v_mfma_f32_16x16x32_bf16 v[78:81], v[154:157], v[232:235], v[78:81]
	v_mfma_f32_16x16x32_bf16 v[78:81], v[158:161], v[236:239], v[78:81]
	v_mfma_f32_16x16x32_bf16 v[94:97], v[158:161], v[228:231], v[94:97]
	v_mfma_f32_16x16x32_bf16 v[94:97], v[154:157], v[206:209], v[94:97]
	v_mfma_f32_16x16x32_bf16 v[110:113], v[154:157], v[198:201], v[110:113]
	v_mfma_f32_16x16x32_bf16 v[110:113], v[158:161], v[202:205], v[110:113]
	v_mfma_f32_16x16x32_bf16 v[122:125], v[158:161], v[194:197], v[122:125]
	v_mfma_f32_16x16x32_bf16 v[122:125], v[154:157], v[190:193], v[122:125]
	s_setprio 0
	s_setprio 1
	v_mfma_f32_16x16x32_bf16 v[114:117], v[162:165], v[190:193], v[114:117]
	v_mfma_f32_16x16x32_bf16 v[114:117], v[166:169], v[194:197], v[114:117]
	v_mfma_f32_16x16x32_bf16 v[98:101], v[166:169], v[202:205], v[98:101]
	v_mfma_f32_16x16x32_bf16 v[98:101], v[162:165], v[198:201], v[98:101]
	v_mfma_f32_16x16x32_bf16 v[82:85], v[162:165], v[206:209], v[82:85]
	v_mfma_f32_16x16x32_bf16 v[82:85], v[166:169], v[228:231], v[82:85]
	v_mfma_f32_16x16x32_bf16 v[70:73], v[166:169], v[236:239], v[70:73]
	v_mfma_f32_16x16x32_bf16 v[70:73], v[162:165], v[232:235], v[70:73]
	v_mfma_f32_16x16x32_bf16 v[66:69], v[170:173], v[232:235], v[66:69]
	v_mfma_f32_16x16x32_bf16 v[66:69], v[178:181], v[236:239], v[66:69]
	v_mfma_f32_16x16x32_bf16 v[74:77], v[178:181], v[228:231], v[74:77]
	v_mfma_f32_16x16x32_bf16 v[74:77], v[170:173], v[206:209], v[74:77]
	v_mfma_f32_16x16x32_bf16 v[90:93], v[170:173], v[198:201], v[90:93]
	v_mfma_f32_16x16x32_bf16 v[90:93], v[178:181], v[202:205], v[90:93]
	v_mfma_f32_16x16x32_bf16 v[106:109], v[178:181], v[194:197], v[106:109]
	v_mfma_f32_16x16x32_bf16 v[106:109], v[170:173], v[190:193], v[106:109]
	s_setprio 0
	s_barrier
	s_add_i32 s53, s53, s38
	v_lshl_add_u64 v[140:141], s[22:23], 0, v[0:1]
	s_mov_b32 m0, s53
	ds_read_b128 v[190:193], v145 offset:16384
	ds_read_b128 v[194:197], v145 offset:16896
	ds_read_b128 v[198:201], v145 offset:18432
	ds_read_b128 v[202:205], v145 offset:18944
	ds_read_b128 v[206:209], v145 offset:20480
	ds_read_b128 v[228:231], v145 offset:20992
	ds_read_b128 v[232:235], v145 offset:22528
	ds_read_b128 v[236:239], v145 offset:23040
	global_load_lds_dwordx4 v[140:141], off
	s_add_i32 m0, s53, 0x2000
	s_add_u32 s54, s22, 0x100000
	v_lshl_add_u64 v[186:187], s[22:23], 0, v[130:131]
	s_addc_u32 s55, s23, 0
	s_add_i32 s53, s56, s38
	global_load_lds_dwordx4 v[186:187], off
	v_lshl_add_u64 v[188:189], s[54:55], 0, v[0:1]
	s_mov_b32 m0, s53
	v_lshl_add_u64 v[210:211], s[24:25], 0, v[132:133]
	global_load_lds_dwordx4 v[188:189], off
	v_lshl_add_u64 v[188:189], s[54:55], 0, v[130:131]
	s_add_i32 m0, s53, 0x2000
	s_nop 0
	global_load_lds_dwordx4 v[188:189], off
	v_lshl_add_u64 v[188:189], s[24:25], 0, v[134:135]
	s_mov_b32 m0, s39
	s_nop 0
	global_load_lds_dwordx4 v[188:189], off
	s_mov_b32 m0, s40
	s_nop 0
	global_load_lds_dwordx4 v[210:211], off
	s_waitcnt vmcnt(8)
	s_waitcnt lgkmcnt(0)
	s_barrier
	s_setprio 1
	s_waitcnt lgkmcnt(0)
	v_mfma_f32_16x16x32_bf16 v[62:65], v[146:149], v[190:193], v[62:65]
	v_mfma_f32_16x16x32_bf16 v[62:65], v[150:153], v[194:197], v[62:65]
	v_mfma_f32_16x16x32_bf16 v[54:57], v[150:153], v[202:205], v[54:57]
	v_mfma_f32_16x16x32_bf16 v[54:57], v[146:149], v[198:201], v[54:57]
	v_mfma_f32_16x16x32_bf16 v[38:41], v[146:149], v[206:209], v[38:41]
	v_mfma_f32_16x16x32_bf16 v[38:41], v[150:153], v[228:231], v[38:41]
	v_mfma_f32_16x16x32_bf16 v[22:25], v[150:153], v[236:239], v[22:25]
	v_mfma_f32_16x16x32_bf16 v[22:25], v[146:149], v[232:235], v[22:25]
	v_mfma_f32_16x16x32_bf16 v[14:17], v[154:157], v[232:235], v[14:17]
	v_mfma_f32_16x16x32_bf16 v[14:17], v[158:161], v[236:239], v[14:17]
	v_mfma_f32_16x16x32_bf16 v[30:33], v[158:161], v[228:231], v[30:33]
	v_mfma_f32_16x16x32_bf16 v[30:33], v[154:157], v[206:209], v[30:33]
	v_mfma_f32_16x16x32_bf16 v[46:49], v[154:157], v[198:201], v[46:49]
	v_mfma_f32_16x16x32_bf16 v[46:49], v[158:161], v[202:205], v[46:49]
	v_mfma_f32_16x16x32_bf16 v[58:61], v[158:161], v[194:197], v[58:61]
	v_mfma_f32_16x16x32_bf16 v[58:61], v[154:157], v[190:193], v[58:61]
	s_setprio 0
	s_setprio 1
	v_mfma_f32_16x16x32_bf16 v[50:53], v[162:165], v[190:193], v[50:53]
	v_mfma_f32_16x16x32_bf16 v[50:53], v[166:169], v[194:197], v[50:53]
	v_mfma_f32_16x16x32_bf16 v[34:37], v[166:169], v[202:205], v[34:37]
	v_mfma_f32_16x16x32_bf16 v[34:37], v[162:165], v[198:201], v[34:37]
	v_mfma_f32_16x16x32_bf16 v[18:21], v[162:165], v[206:209], v[18:21]
	v_mfma_f32_16x16x32_bf16 v[18:21], v[166:169], v[228:231], v[18:21]
	v_mfma_f32_16x16x32_bf16 v[6:9], v[166:169], v[236:239], v[6:9]
	v_mfma_f32_16x16x32_bf16 v[6:9], v[162:165], v[232:235], v[6:9]
	v_mfma_f32_16x16x32_bf16 v[2:5], v[170:173], v[232:235], v[2:5]
	v_mfma_f32_16x16x32_bf16 v[2:5], v[178:181], v[236:239], v[2:5]
	v_mfma_f32_16x16x32_bf16 v[10:13], v[178:181], v[228:231], v[10:13]
	v_mfma_f32_16x16x32_bf16 v[10:13], v[170:173], v[206:209], v[10:13]
	v_mfma_f32_16x16x32_bf16 v[26:29], v[170:173], v[198:201], v[26:29]
	v_mfma_f32_16x16x32_bf16 v[26:29], v[178:181], v[202:205], v[26:29]
	v_mfma_f32_16x16x32_bf16 v[42:45], v[178:181], v[194:197], v[42:45]
	v_mfma_f32_16x16x32_bf16 v[42:45], v[170:173], v[190:193], v[42:45]
	s_setprio 0
	s_barrier
	s_add_i32 s53, 0, 0x18000
	s_add_i32 s54, 0, 0x1c000
	v_add_u32_e32 v158, s53, v143
	v_add_u32_e32 v175, s54, v143
	ds_read_b128 v[146:149], v158
	ds_read_b128 v[150:153], v158 offset:512
	ds_read_b128 v[154:157], v158 offset:2048
	ds_read_b128 v[158:161], v158 offset:2560
	ds_read_b128 v[162:165], v175
	ds_read_b128 v[166:169], v175 offset:512
	ds_read_b128 v[170:173], v175 offset:2048
	ds_read_b128 v[178:181], v175 offset:2560
	s_add_u32 s24, s24, 0x100000
	s_addc_u32 s25, s25, 0
	s_mov_b32 m0, s41
	v_lshl_add_u64 v[226:227], s[24:25], 0, v[134:135]
	ds_read_b128 v[190:193], v145 offset:32768
	ds_read_b128 v[194:197], v145 offset:33280
	ds_read_b128 v[198:201], v145 offset:34816
	ds_read_b128 v[202:205], v145 offset:35328
	ds_read_b128 v[206:209], v145 offset:36864
	ds_read_b128 v[228:231], v145 offset:37376
	ds_read_b128 v[232:235], v145 offset:38912
	ds_read_b128 v[236:239], v145 offset:39424
	global_load_lds_dwordx4 v[226:227], off
	v_lshl_add_u64 v[226:227], s[24:25], 0, v[132:133]
	s_mov_b32 m0, s42
	s_nop 0
	global_load_lds_dwordx4 v[226:227], off
	s_waitcnt vmcnt(8)
	s_waitcnt lgkmcnt(0)
	s_barrier
	s_setprio 1
	s_waitcnt lgkmcnt(0)
	v_mfma_f32_16x16x32_bf16 v[126:129], v[146:149], v[190:193], v[126:129]
	v_mfma_f32_16x16x32_bf16 v[126:129], v[150:153], v[194:197], v[126:129]
	v_mfma_f32_16x16x32_bf16 v[118:121], v[150:153], v[202:205], v[118:121]
	v_mfma_f32_16x16x32_bf16 v[118:121], v[146:149], v[198:201], v[118:121]
	v_mfma_f32_16x16x32_bf16 v[102:105], v[146:149], v[206:209], v[102:105]
	v_mfma_f32_16x16x32_bf16 v[102:105], v[150:153], v[228:231], v[102:105]
	v_mfma_f32_16x16x32_bf16 v[86:89], v[150:153], v[236:239], v[86:89]
	v_mfma_f32_16x16x32_bf16 v[86:89], v[146:149], v[232:235], v[86:89]
	v_mfma_f32_16x16x32_bf16 v[78:81], v[154:157], v[232:235], v[78:81]
	v_mfma_f32_16x16x32_bf16 v[78:81], v[158:161], v[236:239], v[78:81]
	v_mfma_f32_16x16x32_bf16 v[94:97], v[158:161], v[228:231], v[94:97]
	v_mfma_f32_16x16x32_bf16 v[94:97], v[154:157], v[206:209], v[94:97]
	v_mfma_f32_16x16x32_bf16 v[110:113], v[154:157], v[198:201], v[110:113]
	v_mfma_f32_16x16x32_bf16 v[110:113], v[158:161], v[202:205], v[110:113]
	v_mfma_f32_16x16x32_bf16 v[122:125], v[158:161], v[194:197], v[122:125]
	v_mfma_f32_16x16x32_bf16 v[122:125], v[154:157], v[190:193], v[122:125]
	s_setprio 0
	s_setprio 1
	v_mfma_f32_16x16x32_bf16 v[114:117], v[162:165], v[190:193], v[114:117]
	v_mfma_f32_16x16x32_bf16 v[114:117], v[166:169], v[194:197], v[114:117]
	v_mfma_f32_16x16x32_bf16 v[98:101], v[166:169], v[202:205], v[98:101]
	v_mfma_f32_16x16x32_bf16 v[98:101], v[162:165], v[198:201], v[98:101]
	v_mfma_f32_16x16x32_bf16 v[82:85], v[162:165], v[206:209], v[82:85]
	v_mfma_f32_16x16x32_bf16 v[82:85], v[166:169], v[228:231], v[82:85]
	v_mfma_f32_16x16x32_bf16 v[70:73], v[166:169], v[236:239], v[70:73]
	v_mfma_f32_16x16x32_bf16 v[70:73], v[162:165], v[232:235], v[70:73]
	v_mfma_f32_16x16x32_bf16 v[66:69], v[170:173], v[232:235], v[66:69]
	v_mfma_f32_16x16x32_bf16 v[66:69], v[178:181], v[236:239], v[66:69]
	v_mfma_f32_16x16x32_bf16 v[74:77], v[178:181], v[228:231], v[74:77]
	v_mfma_f32_16x16x32_bf16 v[74:77], v[170:173], v[206:209], v[74:77]
	v_mfma_f32_16x16x32_bf16 v[90:93], v[170:173], v[198:201], v[90:93]
	v_mfma_f32_16x16x32_bf16 v[90:93], v[178:181], v[202:205], v[90:93]
	v_mfma_f32_16x16x32_bf16 v[106:109], v[178:181], v[194:197], v[106:109]
	v_mfma_f32_16x16x32_bf16 v[106:109], v[170:173], v[190:193], v[106:109]
	s_setprio 0
	s_barrier
	s_add_i32 s24, s53, s38
	v_lshl_add_u64 v[140:141], v[140:141], 0, s[34:35]
	s_mov_b32 m0, s24
	ds_read_b128 v[190:193], v145 offset:49152
	ds_read_b128 v[194:197], v145 offset:49664
	ds_read_b128 v[198:201], v145 offset:51200
	ds_read_b128 v[202:205], v145 offset:51712
	ds_read_b128 v[206:209], v145 offset:53248
	ds_read_b128 v[228:231], v145 offset:53760
	ds_read_b128 v[232:235], v145 offset:55296
	ds_read_b128 v[236:239], v145 offset:55808
	global_load_lds_dwordx4 v[140:141], off
	s_add_i32 m0, s24, 0x2000
	s_add_u32 s22, s22, 0x100080
	v_lshl_add_u64 v[140:141], v[186:187], 0, s[34:35]
	s_addc_u32 s23, s23, 0
	s_add_i32 s24, s54, s38
	global_load_lds_dwordx4 v[140:141], off
	v_lshl_add_u64 v[140:141], s[22:23], 0, v[0:1]
	s_mov_b32 m0, s24
	s_nop 0
	global_load_lds_dwordx4 v[140:141], off
	v_lshl_add_u64 v[140:141], s[22:23], 0, v[130:131]
	s_add_i32 m0, s24, 0x2000
	s_nop 0
	global_load_lds_dwordx4 v[140:141], off
	v_lshl_add_u64 v[140:141], v[188:189], 0, s[34:35]
	s_mov_b32 m0, s43
	s_nop 0
	global_load_lds_dwordx4 v[140:141], off
	v_lshl_add_u64 v[140:141], v[210:211], 0, s[34:35]
	s_mov_b32 m0, s44
	s_nop 0
	global_load_lds_dwordx4 v[140:141], off
	s_waitcnt vmcnt(8)
	s_waitcnt lgkmcnt(0)
	s_barrier
	s_setprio 1
	s_waitcnt lgkmcnt(0)
	v_mfma_f32_16x16x32_bf16 v[62:65], v[146:149], v[190:193], v[62:65]
	v_mfma_f32_16x16x32_bf16 v[62:65], v[150:153], v[194:197], v[62:65]
	v_mfma_f32_16x16x32_bf16 v[54:57], v[150:153], v[202:205], v[54:57]
	v_mfma_f32_16x16x32_bf16 v[54:57], v[146:149], v[198:201], v[54:57]
	v_mfma_f32_16x16x32_bf16 v[38:41], v[146:149], v[206:209], v[38:41]
	v_mfma_f32_16x16x32_bf16 v[38:41], v[150:153], v[228:231], v[38:41]
	v_mfma_f32_16x16x32_bf16 v[22:25], v[150:153], v[236:239], v[22:25]
	v_mfma_f32_16x16x32_bf16 v[22:25], v[146:149], v[232:235], v[22:25]
	v_mfma_f32_16x16x32_bf16 v[14:17], v[154:157], v[232:235], v[14:17]
	v_mfma_f32_16x16x32_bf16 v[14:17], v[158:161], v[236:239], v[14:17]
	v_mfma_f32_16x16x32_bf16 v[30:33], v[158:161], v[228:231], v[30:33]
	v_mfma_f32_16x16x32_bf16 v[30:33], v[154:157], v[206:209], v[30:33]
	v_mfma_f32_16x16x32_bf16 v[46:49], v[154:157], v[198:201], v[46:49]
	v_mfma_f32_16x16x32_bf16 v[46:49], v[158:161], v[202:205], v[46:49]
	v_mfma_f32_16x16x32_bf16 v[58:61], v[158:161], v[194:197], v[58:61]
	v_mfma_f32_16x16x32_bf16 v[58:61], v[154:157], v[190:193], v[58:61]
	s_setprio 0
	s_setprio 1
	v_mfma_f32_16x16x32_bf16 v[50:53], v[162:165], v[190:193], v[50:53]
	v_mfma_f32_16x16x32_bf16 v[50:53], v[166:169], v[194:197], v[50:53]
	v_mfma_f32_16x16x32_bf16 v[34:37], v[166:169], v[202:205], v[34:37]
	v_mfma_f32_16x16x32_bf16 v[34:37], v[162:165], v[198:201], v[34:37]
	v_mfma_f32_16x16x32_bf16 v[18:21], v[162:165], v[206:209], v[18:21]
	v_mfma_f32_16x16x32_bf16 v[18:21], v[166:169], v[228:231], v[18:21]
	v_mfma_f32_16x16x32_bf16 v[6:9], v[166:169], v[236:239], v[6:9]
	v_mfma_f32_16x16x32_bf16 v[6:9], v[162:165], v[232:235], v[6:9]
	v_mfma_f32_16x16x32_bf16 v[2:5], v[170:173], v[232:235], v[2:5]
	v_mfma_f32_16x16x32_bf16 v[2:5], v[178:181], v[236:239], v[2:5]
	v_mfma_f32_16x16x32_bf16 v[10:13], v[178:181], v[228:231], v[10:13]
	v_mfma_f32_16x16x32_bf16 v[10:13], v[170:173], v[206:209], v[10:13]
	v_mfma_f32_16x16x32_bf16 v[26:29], v[170:173], v[198:201], v[26:29]
	v_mfma_f32_16x16x32_bf16 v[26:29], v[178:181], v[202:205], v[26:29]
	v_mfma_f32_16x16x32_bf16 v[42:45], v[178:181], v[194:197], v[42:45]
	v_mfma_f32_16x16x32_bf16 v[42:45], v[170:173], v[190:193], v[42:45]
	s_setprio 0
	s_barrier
	s_add_i32 s52, s52, 2
	s_add_u32 s18, s18, 0x100
	s_addc_u32 s19, s19, 0
	s_add_u32 s50, s50, 0x100
	s_addc_u32 s51, s51, 0
	s_cmp_gt_u32 s52, 61
	s_cbranch_scc0 .LBB0_575
	s_and_b64 vcc, exec, s[4:5]
	s_cbranch_vccz .LBB0_578
	s_barrier

.LBB0_711:
	s_andn2_b64 vcc, exec, s[0:1]
	s_cbranch_vccnz .LBB0_785
	v_readlane_b32 s0, v253, 25
	v_readlane_b32 s1, v253, 26
	v_readlane_b32 s2, v251, 21
	s_andn2_b64 vcc, exec, s[0:1]
	s_waitcnt vmcnt(0)
	v_mbcnt_lo_u32_b32 v2, -1, 0
	v_mbcnt_hi_u32_b32 v2, -1, v2
	s_cbranch_vccnz .LBB0_728
	v_readlane_b32 s0, v255, 31
	s_add_u32 s24, s0, 0x7200000
	v_readlane_b32 s0, v255, 32
	s_addc_u32 s25, s0, 0
	s_lshl_b32 s26, s2, 10
	v_lshl_add_u32 v0, v2, 4, s26
	v_add_u32_e32 v4, 0x2000, v0
	v_ashrrev_i32_e32 v3, 31, v4
	v_lshrrev_b32_e32 v3, 22, v3
	v_add_u32_e32 v3, v4, v3
	v_ashrrev_i32_e32 v3, 10, v3
	v_mul_i32_i24_e32 v5, 0x400, v3
	v_sub_u32_e32 v4, v4, v5
	v_lshrrev_b32_e32 v5, 4, v4
	v_bitop3_b32 v5, v5, v4, 32 bitop3:0x6c
	v_ashrrev_i32_e32 v4, 31, v5
	v_lshrrev_b32_e32 v4, 26, v4
	v_add_u32_e32 v6, v5, v4
	v_ashrrev_i32_e32 v4, 6, v6
	v_lshlrev_b32_e32 v7, 3, v3
	v_and_b32_e32 v6, 0xffc0, v6
	v_and_b32_e32 v7, -16, v7
	v_sub_u32_e32 v5, v5, v6
	v_add_u32_e32 v7, v4, v7
	v_lshrrev_b16_e32 v6, 7, v5
	v_and_b32_e32 v8, 3, v4
	s_mov_b32 s0, 0x7ffe0
	v_lshrrev_b32_e32 v9, 2, v7
	v_lshlrev_b32_e32 v10, 1, v7
	v_and_b32_e32 v6, 1, v6
	v_and_or_b32 v8, v7, s0, v8
	v_and_b32_e32 v9, 4, v9
	v_and_b32_e32 v10, 24, v10
	v_add_u16_e32 v5, v5, v6
	v_or3_b32 v8, v8, v9, v10
	v_lshlrev_b32_e32 v9, 5, v3
	v_ashrrev_i16_sdwa v5, v212, sext(v5) dst_sel:DWORD dst_unused:UNUSED_PAD src0_sel:DWORD src1_sel:BYTE_0
	v_and_b32_e32 v9, 32, v9
	v_bfe_i32 v5, v5, 0, 16
	v_add_lshl_u32 v6, v9, v5, 1
	v_lshl_add_u32 v130, v8, 13, v6
	v_lshl_add_u32 v132, v7, 13, v6
	v_ashrrev_i32_e32 v6, 31, v0
	v_lshrrev_b32_e32 v6, 22, v6
	v_add_u32_e32 v6, v0, v6
	v_ashrrev_i32_e32 v6, 10, v6
	v_mul_i32_i24_e32 v7, 0x400, v6
	v_sub_u32_e32 v0, v0, v7
	v_lshrrev_b32_e32 v7, 4, v0
	v_bitop3_b32 v0, v7, v0, 32 bitop3:0x6c
	v_ashrrev_i32_e32 v7, 31, v0
	v_lshrrev_b32_e32 v7, 26, v7
	v_add_u32_e32 v8, v0, v7
	v_lshlrev_b32_e32 v9, 3, v6
	v_ashrrev_i32_e32 v7, 6, v8
	v_and_b32_e32 v9, -16, v9
	v_add_u32_e32 v9, v7, v9
	v_and_b32_e32 v10, 3, v7
	v_lshrrev_b32_e32 v11, 2, v9
	v_lshlrev_b32_e32 v12, 1, v9
	v_and_b32_e32 v8, 0xc0, v8
	v_and_or_b32 v10, v9, s0, v10
	v_and_b32_e32 v11, 4, v11
	v_and_b32_e32 v12, 24, v12
	v_sub_u32_e32 v0, v0, v8
	s_ashr_i32 s3, s2, 2
	v_or3_b32 v10, v10, v11, v12
	v_lshlrev_b32_e32 v11, 5, v6
	v_ashrrev_i16_sdwa v0, v212, sext(v0) dst_sel:DWORD dst_unused:UNUSED_PAD src0_sel:DWORD src1_sel:BYTE_0
	v_readlane_b32 s0, v254, 22
	v_and_b32_e32 v11, 32, v11
	v_bfe_i32 v8, v0, 0, 16
	v_readlane_b32 s1, v254, 23
	s_add_u32 s18, s24, s0
	v_add_lshl_u32 v11, v11, v8, 1
	s_addc_u32 s19, s25, s1
	s_add_i32 s31, s26, 0
	v_lshl_add_u32 v0, v10, 13, v11
	s_add_i32 m0, s31, 0x10000
	v_lshl_add_u32 v134, v9, 13, v11
	v_readlane_b32 s56, v251, 21
	v_mbcnt_lo_u32_b32 v103, -1, 0
	v_mbcnt_hi_u32_b32 v103, -1, v103
	v_lshrrev_b32_e32 v100, 2, v103
	v_and_b32_e32 v100, 7, v100
	v_lshrrev_b32_e32 v101, 3, v103
	v_and_b32_e32 v101, 2, v101
	v_and_b32_e32 v102, 3, v103
	v_xor_b32_e32 v101, v101, v102
	v_lshlrev_b32_e32 v101, 4, v101
	v_lshrrev_b32_e32 v102, 5, v103
	v_lshl_or_b32 v101, v102, 6, v101
	s_lshl_b32 s57, s56, 3
	v_add_u32_e32 v102, s57, v100
	v_lshl_add_u32 v134, v102, 13, v101
	v_add_u32_e32 v132, 0x80000, v134
	v_lshrrev_b32_e32 v102, 2, v100
	v_and_b32_e32 v103, 3, v100
	v_lshl_or_b32 v102, v102, 3, v103
	s_lshr_b32 s57, s56, 2
	s_lshl_b32 s57, s57, 5
	s_and_b32 s58, s56, 1
	s_lshl_b32 s58, s58, 4
	s_or_b32 s57, s57, s58
	s_and_b32 s58, s56, 2
	s_lshl_b32 s58, s58, 1
	s_or_b32 s57, s57, s58
	v_add_u32_e32 v102, s57, v102
	v_lshl_add_u32 v0, v102, 13, v101
	v_add_u32_e32 v130, 0x80000, v0
	global_load_lds_dwordx4 v0, s[18:19]
	s_add_i32 m0, s31, 0x12000
	s_add_u32 s0, s18, 0x100000
	global_load_lds_dwordx4 v130, s[18:19]
	s_addc_u32 s1, s19, 0
	s_add_i32 m0, s31, 0x14000
	s_add_i32 s40, s31, 0x2000
	global_load_lds_dwordx4 v0, s[0:1]
	s_add_i32 m0, s31, 0x16000
	s_add_i32 s41, s31, 0x4000
	global_load_lds_dwordx4 v130, s[0:1]
	v_readlane_b32 s0, v254, 26
	s_mov_b32 m0, s31
	v_readlane_b32 s1, v254, 27
	s_add_i32 s42, s31, 0x6000
	s_cmp_eq_u32 s3, 1
	s_nop 2
	global_load_lds_dwordx4 v134, s[0:1]
	s_mov_b32 m0, s40
	s_nop 0
	global_load_lds_dwordx4 v132, s[0:1]
	v_readlane_b32 s0, v254, 28
	s_mov_b32 m0, s41
	v_readlane_b32 s1, v254, 29
	s_nop 4
	global_load_lds_dwordx4 v134, s[0:1]
	s_mov_b32 m0, s42
	s_nop 0
	global_load_lds_dwordx4 v132, s[0:1]
	s_cselect_b64 s[0:1], -1, 0
	s_cmp_lg_u32 s3, 1
	s_cbranch_scc1 .LBB0_715
	s_barrier
.LBB0_715:
	v_lshl_add_u64 v[10:11], s[18:19], 0, v[0:1]
	v_mov_b32_e32 v131, v1
	v_readlane_b32 s16, v254, 26
	s_lshl_b32 s4, s2, 5
	v_lshl_add_u64 v[12:13], s[18:19], 0, v[130:131]
	v_mov_b32_e32 v135, v1
	v_readlane_b32 s17, v254, 27
	s_and_b32 s6, s4, 0x60
	s_add_i32 m0, s31, 0x18000
	v_lshl_add_u64 v[10:11], v[10:11], 0, s[34:35]
	v_lshl_add_u64 v[14:15], s[16:17], 0, v[134:135]
	v_mov_b32_e32 v133, v1
	s_lshr_b32 s7, s6, 3
	s_waitcnt vmcnt(2)
	s_barrier
	global_load_lds_dwordx4 v[10:11], off
	v_lshl_add_u64 v[10:11], v[12:13], 0, s[34:35]
	s_add_i32 m0, s31, 0x1a000
	s_add_i32 s43, s31, 0x8000
	s_add_i32 s44, s31, 0xa000
	v_lshl_add_u64 v[16:17], s[16:17], 0, v[132:133]
	global_load_lds_dwordx4 v[10:11], off
	v_lshl_add_u64 v[10:11], v[14:15], 0, s[34:35]
	s_mov_b32 m0, s43
	s_add_u32 s4, s18, 0x100080
	global_load_lds_dwordx4 v[10:11], off
	v_lshl_add_u64 v[10:11], v[16:17], 0, s[34:35]
	s_mov_b32 m0, s44
	s_addc_u32 s5, s19, 0
	global_load_lds_dwordx4 v[10:11], off
	s_add_i32 m0, s31, 0x1c000
	v_lshl_add_u64 v[10:11], s[4:5], 0, v[0:1]
	global_load_lds_dwordx4 v[10:11], off
	v_lshl_add_u64 v[10:11], s[4:5], 0, v[130:131]
	s_add_i32 m0, s31, 0x1e000
	v_and_b32_e32 v9, 15, v2
	global_load_lds_dwordx4 v[10:11], off
	v_ashrrev_i32_e32 v11, 6, v2
	v_ashrrev_i32_e32 v10, 1, v2
	v_and_b32_e32 v12, 48, v2
	v_lshlrev_b32_e32 v13, 10, v11
	v_lshlrev_b32_e32 v2, 2, v2
	v_lshl_or_b32 v142, s3, 6, v9
	v_lshl_add_u32 v13, s3, 13, v13
	v_lshl_or_b32 v9, v9, 6, v12
	v_and_b32_e32 v2, 32, v2
	v_add_lshl_u32 v11, s7, v11, 10
	v_bitop3_b32 v12, v9, v13, v2 bitop3:0xde
	v_bitop3_b32 v143, v11, v9, v2 bitop3:0xf6
	v_lshlrev_b32_e32 v2, 16, v6
	v_and_b32_e32 v2, 0xfffe0000, v2
	v_lshl_add_u32 v2, v7, 13, v2
	v_and_b32_e32 v6, 1, v6
	v_lshl_or_b32 v2, v6, 6, v2
	v_lshl_add_u32 v136, v8, 1, v2
	v_lshlrev_b32_e32 v2, 16, v3
	v_and_b32_e32 v2, 0xfffe0000, v2
	s_waitcnt vmcnt(6)
	v_lshl_add_u32 v2, v4, 13, v2
	v_and_b32_e32 v3, 1, v3
	v_and_b32_e32 v10, -8, v10
	s_cmp_lt_u32 s2, 4
	v_lshl_or_b32 v2, v3, 6, v2
	v_readlane_b32 s4, v254, 24
	s_cselect_b64 s[2:3], -1, 0
	v_add_u32_e32 v144, s6, v10
	v_mov_b32_e32 v137, v1
	v_lshl_add_u32 v138, v5, 1, v2
	v_mov_b32_e32 v139, v1
	s_mov_b32 s45, 0
	v_add_u32_e32 v145, 0, v12
	v_readlane_b32 s46, v254, 21
	s_mov_b32 s47, s4
	s_barrier
	v_readlane_b32 s5, v254, 25
	v_readlane_b32 s56, v251, 21
	v_mbcnt_lo_u32_b32 v100, -1, 0
	v_mbcnt_hi_u32_b32 v100, -1, v100
	v_and_b32_e32 v101, 15, v100
	v_lshrrev_b32_e32 v102, 4, v100
	v_lshrrev_b32_e32 v103, 1, v101
	v_and_b32_e32 v103, 2, v103
	v_xor_b32_e32 v102, v102, v103
	v_lshlrev_b32_e32 v102, 4, v102
	v_and_b32_e32 v103, 7, v101
	v_lshl_or_b32 v102, v103, 6, v102
	v_lshrrev_b32_e32 v103, 3, v101
	v_lshl_or_b32 v102, v103, 10, v102
	s_lshr_b32 s57, s56, 2
	s_lshl_b32 s57, s57, 13
	v_add_u32_e32 v145, s57, v102
	s_and_b32 s57, s56, 3
	s_lshl_b32 s57, s57, 12
	v_add_u32_e32 v143, s57, v102
	v_mov_b32_e32 v136, v134
	v_mov_b32_e32 v138, v132
	s_branch .LBB0_718

.LBB0_721:
	s_add_u32 s18, s16, 0xfff00080
	s_addc_u32 s19, s17, -1
	s_add_i32 s53, 0, 0x10000
	s_cmp_eq_u32 s52, 60
	s_cselect_b32 s23, s7, s19
	s_cselect_b32 s22, s48, s18
	v_add_u32_e32 v140, s53, v143
	s_cselect_b32 s19, s5, s51
	s_cselect_b32 s18, s49, s50
	s_add_i32 s56, 0, 0x14000
	ds_read_b128 v[146:149], v140
	ds_read_b128 v[150:153], v140 offset:512
	ds_read_b128 v[154:157], v140 offset:2048
	ds_read_b128 v[158:161], v140 offset:2560
	v_add_u32_e32 v140, s56, v143
	ds_read_b128 v[162:165], v140
	ds_read_b128 v[166:169], v140 offset:512
	ds_read_b128 v[170:173], v140 offset:2048
	ds_read_b128 v[178:181], v140 offset:2560
	v_lshl_add_u64 v[140:141], s[16:17], 0, v[136:137]
	s_add_i32 m0, s31, 0xc000
	ds_read_b128 v[190:193], v145
	ds_read_b128 v[194:197], v145 offset:512
	ds_read_b128 v[198:201], v145 offset:2048
	ds_read_b128 v[202:205], v145 offset:2560
	ds_read_b128 v[206:209], v145 offset:4096
	ds_read_b128 v[228:231], v145 offset:4608
	ds_read_b128 v[232:235], v145 offset:6144
	ds_read_b128 v[236:239], v145 offset:6656
	global_load_lds_dwordx4 v[140:141], off
	v_lshl_add_u64 v[140:141], s[16:17], 0, v[138:139]
	s_add_i32 m0, s31, 0xe000
	s_nop 0
	global_load_lds_dwordx4 v[140:141], off
	s_waitcnt vmcnt(8)
	s_waitcnt lgkmcnt(0)
	s_barrier
	s_setprio 1
	s_waitcnt lgkmcnt(0)
	v_mfma_f32_16x16x32_bf16 v[126:129], v[146:149], v[190:193], v[126:129]
	v_mfma_f32_16x16x32_bf16 v[126:129], v[150:153], v[194:197], v[126:129]
	v_mfma_f32_16x16x32_bf16 v[110:113], v[150:153], v[202:205], v[110:113]
	v_mfma_f32_16x16x32_bf16 v[110:113], v[146:149], v[198:201], v[110:113]
	v_mfma_f32_16x16x32_bf16 v[94:97], v[146:149], v[206:209], v[94:97]
	v_mfma_f32_16x16x32_bf16 v[94:97], v[150:153], v[228:231], v[94:97]
	v_mfma_f32_16x16x32_bf16 v[78:81], v[150:153], v[236:239], v[78:81]
	v_mfma_f32_16x16x32_bf16 v[78:81], v[146:149], v[232:235], v[78:81]
	v_mfma_f32_16x16x32_bf16 v[70:73], v[154:157], v[232:235], v[70:73]
	v_mfma_f32_16x16x32_bf16 v[70:73], v[158:161], v[236:239], v[70:73]
	v_mfma_f32_16x16x32_bf16 v[86:89], v[158:161], v[228:231], v[86:89]
	v_mfma_f32_16x16x32_bf16 v[86:89], v[154:157], v[206:209], v[86:89]
	v_mfma_f32_16x16x32_bf16 v[102:105], v[154:157], v[198:201], v[102:105]
	v_mfma_f32_16x16x32_bf16 v[102:105], v[158:161], v[202:205], v[102:105]
	v_mfma_f32_16x16x32_bf16 v[118:121], v[158:161], v[194:197], v[118:121]
	v_mfma_f32_16x16x32_bf16 v[118:121], v[154:157], v[190:193], v[118:121]
	s_setprio 0
	s_setprio 1
	v_mfma_f32_16x16x32_bf16 v[122:125], v[162:165], v[190:193], v[122:125]
	v_mfma_f32_16x16x32_bf16 v[122:125], v[166:169], v[194:197], v[122:125]
	v_mfma_f32_16x16x32_bf16 v[106:109], v[166:169], v[202:205], v[106:109]
	v_mfma_f32_16x16x32_bf16 v[106:109], v[162:165], v[198:201], v[106:109]
	v_mfma_f32_16x16x32_bf16 v[90:93], v[162:165], v[206:209], v[90:93]
	v_mfma_f32_16x16x32_bf16 v[90:93], v[166:169], v[228:231], v[90:93]
	v_mfma_f32_16x16x32_bf16 v[74:77], v[166:169], v[236:239], v[74:77]
	v_mfma_f32_16x16x32_bf16 v[74:77], v[162:165], v[232:235], v[74:77]
	v_mfma_f32_16x16x32_bf16 v[66:69], v[170:173], v[232:235], v[66:69]
	v_mfma_f32_16x16x32_bf16 v[66:69], v[178:181], v[236:239], v[66:69]
	v_mfma_f32_16x16x32_bf16 v[82:85], v[178:181], v[228:231], v[82:85]
	v_mfma_f32_16x16x32_bf16 v[82:85], v[170:173], v[206:209], v[82:85]
	v_mfma_f32_16x16x32_bf16 v[98:101], v[170:173], v[198:201], v[98:101]
	v_mfma_f32_16x16x32_bf16 v[98:101], v[178:181], v[202:205], v[98:101]
	v_mfma_f32_16x16x32_bf16 v[114:117], v[178:181], v[194:197], v[114:117]
	v_mfma_f32_16x16x32_bf16 v[114:117], v[170:173], v[190:193], v[114:117]
	s_setprio 0
	s_barrier
	s_add_i32 s53, s53, s26
	v_lshl_add_u64 v[140:141], s[18:19], 0, v[0:1]
	s_mov_b32 m0, s53
	ds_read_b128 v[190:193], v145 offset:16384
	ds_read_b128 v[194:197], v145 offset:16896
	ds_read_b128 v[198:201], v145 offset:18432
	ds_read_b128 v[202:205], v145 offset:18944
	ds_read_b128 v[206:209], v145 offset:20480
	ds_read_b128 v[228:231], v145 offset:20992
	ds_read_b128 v[232:235], v145 offset:22528
	ds_read_b128 v[236:239], v145 offset:23040
	global_load_lds_dwordx4 v[140:141], off
	s_add_i32 m0, s53, 0x2000
	s_add_u32 s54, s18, 0x100000
	v_lshl_add_u64 v[186:187], s[18:19], 0, v[130:131]
	s_addc_u32 s55, s19, 0
	s_add_i32 s53, s56, s26
	global_load_lds_dwordx4 v[186:187], off
	v_lshl_add_u64 v[188:189], s[54:55], 0, v[0:1]
	s_mov_b32 m0, s53
	v_lshl_add_u64 v[210:211], s[22:23], 0, v[132:133]
	global_load_lds_dwordx4 v[188:189], off
	v_lshl_add_u64 v[188:189], s[54:55], 0, v[130:131]
	s_add_i32 m0, s53, 0x2000
	s_nop 0
	global_load_lds_dwordx4 v[188:189], off
	v_lshl_add_u64 v[188:189], s[22:23], 0, v[134:135]
	s_mov_b32 m0, s31
	s_nop 0
	global_load_lds_dwordx4 v[188:189], off
	s_mov_b32 m0, s40
	s_nop 0
	global_load_lds_dwordx4 v[210:211], off
	s_waitcnt vmcnt(8)
	s_waitcnt lgkmcnt(0)
	s_barrier
	s_setprio 1
	s_waitcnt lgkmcnt(0)
	v_mfma_f32_16x16x32_bf16 v[62:65], v[146:149], v[190:193], v[62:65]
	v_mfma_f32_16x16x32_bf16 v[62:65], v[150:153], v[194:197], v[62:65]
	v_mfma_f32_16x16x32_bf16 v[46:49], v[150:153], v[202:205], v[46:49]
	v_mfma_f32_16x16x32_bf16 v[46:49], v[146:149], v[198:201], v[46:49]
	v_mfma_f32_16x16x32_bf16 v[30:33], v[146:149], v[206:209], v[30:33]
	v_mfma_f32_16x16x32_bf16 v[30:33], v[150:153], v[228:231], v[30:33]
	v_mfma_f32_16x16x32_bf16 v[14:17], v[150:153], v[236:239], v[14:17]
	v_mfma_f32_16x16x32_bf16 v[14:17], v[146:149], v[232:235], v[14:17]
	v_mfma_f32_16x16x32_bf16 v[6:9], v[154:157], v[232:235], v[6:9]
	v_mfma_f32_16x16x32_bf16 v[6:9], v[158:161], v[236:239], v[6:9]
	v_mfma_f32_16x16x32_bf16 v[22:25], v[158:161], v[228:231], v[22:25]
	v_mfma_f32_16x16x32_bf16 v[22:25], v[154:157], v[206:209], v[22:25]
	v_mfma_f32_16x16x32_bf16 v[38:41], v[154:157], v[198:201], v[38:41]
	v_mfma_f32_16x16x32_bf16 v[38:41], v[158:161], v[202:205], v[38:41]
	v_mfma_f32_16x16x32_bf16 v[54:57], v[158:161], v[194:197], v[54:57]
	v_mfma_f32_16x16x32_bf16 v[54:57], v[154:157], v[190:193], v[54:57]
	s_setprio 0
	s_setprio 1
	v_mfma_f32_16x16x32_bf16 v[58:61], v[162:165], v[190:193], v[58:61]
	v_mfma_f32_16x16x32_bf16 v[58:61], v[166:169], v[194:197], v[58:61]
	v_mfma_f32_16x16x32_bf16 v[42:45], v[166:169], v[202:205], v[42:45]
	v_mfma_f32_16x16x32_bf16 v[42:45], v[162:165], v[198:201], v[42:45]
	v_mfma_f32_16x16x32_bf16 v[26:29], v[162:165], v[206:209], v[26:29]
	v_mfma_f32_16x16x32_bf16 v[26:29], v[166:169], v[228:231], v[26:29]
	v_mfma_f32_16x16x32_bf16 v[10:13], v[166:169], v[236:239], v[10:13]
	v_mfma_f32_16x16x32_bf16 v[10:13], v[162:165], v[232:235], v[10:13]
	v_mfma_f32_16x16x32_bf16 v[2:5], v[170:173], v[232:235], v[2:5]
	v_mfma_f32_16x16x32_bf16 v[2:5], v[178:181], v[236:239], v[2:5]
	v_mfma_f32_16x16x32_bf16 v[18:21], v[178:181], v[228:231], v[18:21]
	v_mfma_f32_16x16x32_bf16 v[18:21], v[170:173], v[206:209], v[18:21]
	v_mfma_f32_16x16x32_bf16 v[34:37], v[170:173], v[198:201], v[34:37]
	v_mfma_f32_16x16x32_bf16 v[34:37], v[178:181], v[202:205], v[34:37]
	v_mfma_f32_16x16x32_bf16 v[50:53], v[178:181], v[194:197], v[50:53]
	v_mfma_f32_16x16x32_bf16 v[50:53], v[170:173], v[190:193], v[50:53]
	s_setprio 0
	s_barrier
	s_add_i32 s53, 0, 0x18000
	s_add_i32 s54, 0, 0x1c000
	v_add_u32_e32 v158, s53, v143
	v_add_u32_e32 v175, s54, v143
	ds_read_b128 v[146:149], v158
	ds_read_b128 v[150:153], v158 offset:512
	ds_read_b128 v[154:157], v158 offset:2048
	ds_read_b128 v[158:161], v158 offset:2560
	ds_read_b128 v[162:165], v175
	ds_read_b128 v[166:169], v175 offset:512
	ds_read_b128 v[170:173], v175 offset:2048
	ds_read_b128 v[178:181], v175 offset:2560
	s_add_u32 s22, s22, 0x100000
	s_addc_u32 s23, s23, 0
	s_mov_b32 m0, s41
	v_lshl_add_u64 v[226:227], s[22:23], 0, v[134:135]
	ds_read_b128 v[190:193], v145 offset:32768
	ds_read_b128 v[194:197], v145 offset:33280
	ds_read_b128 v[198:201], v145 offset:34816
	ds_read_b128 v[202:205], v145 offset:35328
	ds_read_b128 v[206:209], v145 offset:36864
	ds_read_b128 v[228:231], v145 offset:37376
	ds_read_b128 v[232:235], v145 offset:38912
	ds_read_b128 v[236:239], v145 offset:39424
	global_load_lds_dwordx4 v[226:227], off
	v_lshl_add_u64 v[226:227], s[22:23], 0, v[132:133]
	s_mov_b32 m0, s42
	s_nop 0
	global_load_lds_dwordx4 v[226:227], off
	s_waitcnt vmcnt(8)
	s_waitcnt lgkmcnt(0)
	s_barrier
	s_setprio 1
	s_waitcnt lgkmcnt(0)
	v_mfma_f32_16x16x32_bf16 v[126:129], v[146:149], v[190:193], v[126:129]
	v_mfma_f32_16x16x32_bf16 v[126:129], v[150:153], v[194:197], v[126:129]
	v_mfma_f32_16x16x32_bf16 v[110:113], v[150:153], v[202:205], v[110:113]
	v_mfma_f32_16x16x32_bf16 v[110:113], v[146:149], v[198:201], v[110:113]
	v_mfma_f32_16x16x32_bf16 v[94:97], v[146:149], v[206:209], v[94:97]
	v_mfma_f32_16x16x32_bf16 v[94:97], v[150:153], v[228:231], v[94:97]
	v_mfma_f32_16x16x32_bf16 v[78:81], v[150:153], v[236:239], v[78:81]
	v_mfma_f32_16x16x32_bf16 v[78:81], v[146:149], v[232:235], v[78:81]
	v_mfma_f32_16x16x32_bf16 v[70:73], v[154:157], v[232:235], v[70:73]
	v_mfma_f32_16x16x32_bf16 v[70:73], v[158:161], v[236:239], v[70:73]
	v_mfma_f32_16x16x32_bf16 v[86:89], v[158:161], v[228:231], v[86:89]
	v_mfma_f32_16x16x32_bf16 v[86:89], v[154:157], v[206:209], v[86:89]
	v_mfma_f32_16x16x32_bf16 v[102:105], v[154:157], v[198:201], v[102:105]
	v_mfma_f32_16x16x32_bf16 v[102:105], v[158:161], v[202:205], v[102:105]
	v_mfma_f32_16x16x32_bf16 v[118:121], v[158:161], v[194:197], v[118:121]
	v_mfma_f32_16x16x32_bf16 v[118:121], v[154:157], v[190:193], v[118:121]
	s_setprio 0
	s_setprio 1
	v_mfma_f32_16x16x32_bf16 v[122:125], v[162:165], v[190:193], v[122:125]
	v_mfma_f32_16x16x32_bf16 v[122:125], v[166:169], v[194:197], v[122:125]
	v_mfma_f32_16x16x32_bf16 v[106:109], v[166:169], v[202:205], v[106:109]
	v_mfma_f32_16x16x32_bf16 v[106:109], v[162:165], v[198:201], v[106:109]
	v_mfma_f32_16x16x32_bf16 v[90:93], v[162:165], v[206:209], v[90:93]
	v_mfma_f32_16x16x32_bf16 v[90:93], v[166:169], v[228:231], v[90:93]
	v_mfma_f32_16x16x32_bf16 v[74:77], v[166:169], v[236:239], v[74:77]
	v_mfma_f32_16x16x32_bf16 v[74:77], v[162:165], v[232:235], v[74:77]
	v_mfma_f32_16x16x32_bf16 v[66:69], v[170:173], v[232:235], v[66:69]
	v_mfma_f32_16x16x32_bf16 v[66:69], v[178:181], v[236:239], v[66:69]
	v_mfma_f32_16x16x32_bf16 v[82:85], v[178:181], v[228:231], v[82:85]
	v_mfma_f32_16x16x32_bf16 v[82:85], v[170:173], v[206:209], v[82:85]
	v_mfma_f32_16x16x32_bf16 v[98:101], v[170:173], v[198:201], v[98:101]
	v_mfma_f32_16x16x32_bf16 v[98:101], v[178:181], v[202:205], v[98:101]
	v_mfma_f32_16x16x32_bf16 v[114:117], v[178:181], v[194:197], v[114:117]
	v_mfma_f32_16x16x32_bf16 v[114:117], v[170:173], v[190:193], v[114:117]
	s_setprio 0
	s_barrier
	s_add_i32 s22, s53, s26
	v_lshl_add_u64 v[140:141], v[140:141], 0, s[34:35]
	s_mov_b32 m0, s22
	ds_read_b128 v[190:193], v145 offset:49152
	ds_read_b128 v[194:197], v145 offset:49664
	ds_read_b128 v[198:201], v145 offset:51200
	ds_read_b128 v[202:205], v145 offset:51712
	ds_read_b128 v[206:209], v145 offset:53248
	ds_read_b128 v[228:231], v145 offset:53760
	ds_read_b128 v[232:235], v145 offset:55296
	ds_read_b128 v[236:239], v145 offset:55808
	global_load_lds_dwordx4 v[140:141], off
	s_add_i32 m0, s22, 0x2000
	s_add_u32 s18, s18, 0x100080
	v_lshl_add_u64 v[140:141], v[186:187], 0, s[34:35]
	s_addc_u32 s19, s19, 0
	s_add_i32 s22, s54, s26
	global_load_lds_dwordx4 v[140:141], off
	v_lshl_add_u64 v[140:141], s[18:19], 0, v[0:1]
	s_mov_b32 m0, s22
	s_nop 0
	global_load_lds_dwordx4 v[140:141], off
	v_lshl_add_u64 v[140:141], s[18:19], 0, v[130:131]
	s_add_i32 m0, s22, 0x2000
	s_nop 0
	global_load_lds_dwordx4 v[140:141], off
	v_lshl_add_u64 v[140:141], v[188:189], 0, s[34:35]
	s_mov_b32 m0, s43
	s_nop 0
	global_load_lds_dwordx4 v[140:141], off
	v_lshl_add_u64 v[140:141], v[210:211], 0, s[34:35]
	s_mov_b32 m0, s44
	s_nop 0
	global_load_lds_dwordx4 v[140:141], off
	s_waitcnt vmcnt(8)
	s_waitcnt lgkmcnt(0)
	s_barrier
	s_setprio 1
	s_waitcnt lgkmcnt(0)
	v_mfma_f32_16x16x32_bf16 v[62:65], v[146:149], v[190:193], v[62:65]
	v_mfma_f32_16x16x32_bf16 v[62:65], v[150:153], v[194:197], v[62:65]
	v_mfma_f32_16x16x32_bf16 v[46:49], v[150:153], v[202:205], v[46:49]
	v_mfma_f32_16x16x32_bf16 v[46:49], v[146:149], v[198:201], v[46:49]
	v_mfma_f32_16x16x32_bf16 v[30:33], v[146:149], v[206:209], v[30:33]
	v_mfma_f32_16x16x32_bf16 v[30:33], v[150:153], v[228:231], v[30:33]
	v_mfma_f32_16x16x32_bf16 v[14:17], v[150:153], v[236:239], v[14:17]
	v_mfma_f32_16x16x32_bf16 v[14:17], v[146:149], v[232:235], v[14:17]
	v_mfma_f32_16x16x32_bf16 v[6:9], v[154:157], v[232:235], v[6:9]
	v_mfma_f32_16x16x32_bf16 v[6:9], v[158:161], v[236:239], v[6:9]
	v_mfma_f32_16x16x32_bf16 v[22:25], v[158:161], v[228:231], v[22:25]
	v_mfma_f32_16x16x32_bf16 v[22:25], v[154:157], v[206:209], v[22:25]
	v_mfma_f32_16x16x32_bf16 v[38:41], v[154:157], v[198:201], v[38:41]
	v_mfma_f32_16x16x32_bf16 v[38:41], v[158:161], v[202:205], v[38:41]
	v_mfma_f32_16x16x32_bf16 v[54:57], v[158:161], v[194:197], v[54:57]
	v_mfma_f32_16x16x32_bf16 v[54:57], v[154:157], v[190:193], v[54:57]
	s_setprio 0
	s_setprio 1
	v_mfma_f32_16x16x32_bf16 v[58:61], v[162:165], v[190:193], v[58:61]
	v_mfma_f32_16x16x32_bf16 v[58:61], v[166:169], v[194:197], v[58:61]
	v_mfma_f32_16x16x32_bf16 v[42:45], v[166:169], v[202:205], v[42:45]
	v_mfma_f32_16x16x32_bf16 v[42:45], v[162:165], v[198:201], v[42:45]
	v_mfma_f32_16x16x32_bf16 v[26:29], v[162:165], v[206:209], v[26:29]
	v_mfma_f32_16x16x32_bf16 v[26:29], v[166:169], v[228:231], v[26:29]
	v_mfma_f32_16x16x32_bf16 v[10:13], v[166:169], v[236:239], v[10:13]
	v_mfma_f32_16x16x32_bf16 v[10:13], v[162:165], v[232:235], v[10:13]
	v_mfma_f32_16x16x32_bf16 v[2:5], v[170:173], v[232:235], v[2:5]
	v_mfma_f32_16x16x32_bf16 v[2:5], v[178:181], v[236:239], v[2:5]
	v_mfma_f32_16x16x32_bf16 v[18:21], v[178:181], v[228:231], v[18:21]
	v_mfma_f32_16x16x32_bf16 v[18:21], v[170:173], v[206:209], v[18:21]
	v_mfma_f32_16x16x32_bf16 v[34:37], v[170:173], v[198:201], v[34:37]
	v_mfma_f32_16x16x32_bf16 v[34:37], v[178:181], v[202:205], v[34:37]
	v_mfma_f32_16x16x32_bf16 v[50:53], v[178:181], v[194:197], v[50:53]
	v_mfma_f32_16x16x32_bf16 v[50:53], v[170:173], v[190:193], v[50:53]
	s_setprio 0
	s_barrier
	s_add_i32 s52, s52, 2
	s_add_u32 s16, s16, 0x100
	s_addc_u32 s17, s17, 0
	s_add_u32 s50, s50, 0x100
	s_addc_u32 s51, s51, 0
	s_cmp_gt_u32 s52, 61
	s_cbranch_scc0 .LBB0_721
	s_and_b64 vcc, exec, s[2:3]
	s_cbranch_vccz .LBB0_724
	s_barrier
